# shorten barrier-to-MFMA paths: drop redundant lgkmcnt(0) after pre-MFMA barrier, setprio 1 before / setprio 0 after the barriers
# speedup vs baseline: 1.0303x; 1.0303x over previous
; #define PG8_STAGE(bufoff, gbase, voff) do { _Pragma("unroll") for (int _i = 0; _i < 2; ++_i) \
;         __builtin_amdgcn_global_load_lds((const unsigned*)((const char*)(gbase) + (voff)[_i]), (PG8_LAS unsigned*)(lds + (bufoff) + ldsw + _i * 8192), 16, 0, 0); } while (0)
; #define PG8_LDA(dst, b, h) do { _Pragma("unroll") for (int m = 0; m < 4; ++m) _Pragma("unroll") for (int k = 0; k < 2; ++k) dst[m][k] = *(const PG8_LAS bf16x8*)(lds + PG8_SA(b, h) + aoff + m * 2048 + k * 1024); } while (0)
; #define PG8_LDB(dst, b, h) do { _Pragma("unroll") for (int n = 0; n < 2; ++n) _Pragma("unroll") for (int k = 0; k < 2; ++k) dst[n][k] = *(const PG8_LAS bf16x8*)(lds + PG8_SB(b, h) + boff + n * 2048 + k * 1024); } while (0)
; #define PG8_MMA(ai, bj, At, Bt) do { __builtin_amdgcn_s_setprio(1); _Pragma("unroll") for (int m = 0; m < 4; ++m) _Pragma("unroll") for (int n = 0; n < 2; ++n) _Pragma("unroll") for (int k = 0; k < 2; ++k) \
;         acc[ai][bj][m][n] = __builtin_amdgcn_mfma_f32_16x16x32_bf16(Bt[n][k], At[m][k], acc[ai][bj][m][n], 0, 0, 0); __builtin_amdgcn_s_setprio(0); } while (0)
; #define PG8_WAIT_V(n) asm volatile("s_waitcnt vmcnt(" #n ")" ::: "memory")
; #define PG8_WAIT_L(n) asm volatile("s_waitcnt lgkmcnt(" #n ")" ::: "memory")
; #define PG8_BAR __builtin_amdgcn_s_barrier()
; #define PG8_SCHED __builtin_amdgcn_sched_barrier(0)
; template <class Epi, class Sched, bool ALIGN_EPI = false, bool SP2 = false>
; __device__ __forceinline__ void gemm_phase(PG8_LAS unsigned char* lds, const Gemm g, const Sched& S, const Epi& E) {
;     ...
;             const bool last = (t == nt - 2);
;             const char* a1 = cA + (size_t)(t + 1) * kstep;
;             const char* a2 = last ? nA : cA + (size_t)(t + 2) * kstep; const char* b2 = last ? nB : cB + (size_t)(t + 2) * kstep;
;             const char* a3 = a2 + kstep; const char* b3 = b2 + kstep;
;             if (last && has_next) S.a_ready(nxt);
;             if constexpr (SP2) {
;             PG8_LDB(B0, 0, 0); PG8_LDB(B1, 0, 1); PG8_SCHED; PG8_LDA(At, 0, 0); PG8_STAGE(PG8_SA(1, 1), a1 + hstep, voffA);
;             PG8_WAIT_V(8); PG8_WAIT_L(0); PG8_BAR; PG8_MMA(0, 0, At, B0); PG8_MMA(0, 1, At, B1); PG8_BAR; PG8_SCHED;
;             PG8_LDA(At, 0, 1); PG8_STAGE(PG8_SB(0, 0), b2, voffB); PG8_STAGE(PG8_SB(0, 1), b2 + hstep, voffB); PG8_STAGE(PG8_SA(0, 0), a2, voffA);
.LBB0_63:
	s_add_i32 s66, s46, 2
	s_add_u32 s10, s44, 0x80
	s_addc_u32 s11, s45, 0
	s_add_i32 s67, 0, 0x10000
	s_cmp_eq_u32 s74, s46
	s_cselect_b32 s47, s63, s11
	s_cselect_b32 s46, s62, s10
	s_cselect_b32 s79, s65, s20
	s_cselect_b32 s78, s64, s19
	s_add_i32 s10, 0, 0x14000
	v_add_u32_e32 v140, s67, v183
	v_add_u32_e32 v166, s10, v183
	ds_read_b128 v[128:131], v140
	ds_read_b128 v[132:135], v140 offset:1024
	ds_read_b128 v[136:139], v140 offset:2048
	ds_read_b128 v[140:143], v140 offset:3072
	ds_read_b128 v[144:147], v166
	ds_read_b128 v[148:151], v166 offset:1024
	ds_read_b128 v[152:155], v166 offset:2048
	ds_read_b128 v[166:169], v166 offset:3072
	v_lshl_add_u64 v[190:191], s[44:45], 0, v[162:163]
	s_add_i32 m0, s23, 0xc000
	ds_read_b128 v[170:173], v185
	ds_read_b128 v[174:177], v185 offset:1024
	ds_read_b128 v[178:181], v185 offset:2048
	ds_read_b128 v[186:189], v185 offset:3072
	ds_read_b128 v[194:197], v185 offset:4096
	ds_read_b128 v[198:201], v185 offset:5120
	ds_read_b128 v[202:205], v185 offset:6144
	ds_read_b128 v[206:209], v185 offset:7168
	global_load_lds_dwordx4 v[190:191], off
	v_lshl_add_u64 v[190:191], s[44:45], 0, v[164:165]
	s_add_i32 m0, s23, 0xe000
	s_nop 0
	global_load_lds_dwordx4 v[190:191], off
	s_waitcnt vmcnt(8)
	s_waitcnt lgkmcnt(0)
	s_setprio 1
	s_barrier
	v_mfma_f32_16x16x32_bf16 v[124:127], v[128:131], v[170:173], v[124:127]
	v_mfma_f32_16x16x32_bf16 v[120:123], v[136:139], v[170:173], v[120:123]
	v_mfma_f32_16x16x32_bf16 v[108:111], v[128:131], v[178:181], v[108:111]
	v_mfma_f32_16x16x32_bf16 v[104:107], v[136:139], v[178:181], v[104:107]
	v_mfma_f32_16x16x32_bf16 v[92:95], v[128:131], v[194:197], v[92:95]
	v_mfma_f32_16x16x32_bf16 v[88:91], v[136:139], v[194:197], v[88:91]
	v_mfma_f32_16x16x32_bf16 v[76:79], v[128:131], v[202:205], v[76:79]
	v_mfma_f32_16x16x32_bf16 v[72:75], v[136:139], v[202:205], v[72:75]
	v_mfma_f32_16x16x32_bf16 v[124:127], v[132:135], v[174:177], v[124:127]
	v_mfma_f32_16x16x32_bf16 v[120:123], v[140:143], v[174:177], v[120:123]
	v_mfma_f32_16x16x32_bf16 v[108:111], v[132:135], v[186:189], v[108:111]
	v_mfma_f32_16x16x32_bf16 v[104:107], v[140:143], v[186:189], v[104:107]
	v_mfma_f32_16x16x32_bf16 v[92:95], v[132:135], v[198:201], v[92:95]
	v_mfma_f32_16x16x32_bf16 v[88:91], v[140:143], v[198:201], v[88:91]
	v_mfma_f32_16x16x32_bf16 v[76:79], v[132:135], v[206:209], v[76:79]
	v_mfma_f32_16x16x32_bf16 v[72:75], v[140:143], v[206:209], v[72:75]
	s_setprio 0
	s_setprio 1
	v_mfma_f32_16x16x32_bf16 v[116:119], v[144:147], v[170:173], v[116:119]
	v_mfma_f32_16x16x32_bf16 v[112:115], v[152:155], v[170:173], v[112:115]
	v_mfma_f32_16x16x32_bf16 v[100:103], v[144:147], v[178:181], v[100:103]
	v_mfma_f32_16x16x32_bf16 v[96:99], v[152:155], v[178:181], v[96:99]
	v_mfma_f32_16x16x32_bf16 v[84:87], v[144:147], v[194:197], v[84:87]
	v_mfma_f32_16x16x32_bf16 v[80:83], v[152:155], v[194:197], v[80:83]
	v_mfma_f32_16x16x32_bf16 v[68:71], v[144:147], v[202:205], v[68:71]
	v_mfma_f32_16x16x32_bf16 v[64:67], v[152:155], v[202:205], v[64:67]
	v_mfma_f32_16x16x32_bf16 v[116:119], v[148:151], v[174:177], v[116:119]
	v_mfma_f32_16x16x32_bf16 v[112:115], v[166:169], v[174:177], v[112:115]
	v_mfma_f32_16x16x32_bf16 v[100:103], v[148:151], v[186:189], v[100:103]
	v_mfma_f32_16x16x32_bf16 v[96:99], v[166:169], v[186:189], v[96:99]
	v_mfma_f32_16x16x32_bf16 v[84:87], v[148:151], v[198:201], v[84:87]
	v_mfma_f32_16x16x32_bf16 v[80:83], v[166:169], v[198:201], v[80:83]
	v_mfma_f32_16x16x32_bf16 v[68:71], v[148:151], v[206:209], v[68:71]
	v_mfma_f32_16x16x32_bf16 v[64:67], v[166:169], v[206:209], v[64:67]
	s_barrier
	s_setprio 0
	s_add_i32 s11, s67, s22
	v_lshl_add_u64 v[190:191], s[78:79], 0, v[192:193]
	s_mov_b32 m0, s11
	ds_read_b128 v[170:173], v185 offset:16384
	ds_read_b128 v[174:177], v185 offset:17408
	ds_read_b128 v[178:181], v185 offset:18432
	ds_read_b128 v[186:189], v185 offset:19456
	ds_read_b128 v[194:197], v185 offset:20480
	ds_read_b128 v[198:201], v185 offset:21504
	ds_read_b128 v[202:205], v185 offset:22528
	ds_read_b128 v[206:209], v185 offset:23552
	global_load_lds_dwordx4 v[190:191], off
	s_add_i32 m0, s11, 0x2000
	v_lshl_add_u64 v[210:211], s[78:79], 0, v[160:161]
	s_add_u32 s78, s78, s52
	s_addc_u32 s79, s79, 0
	s_add_i32 s10, s10, s22
	global_load_lds_dwordx4 v[210:211], off
	v_lshl_add_u64 v[212:213], s[78:79], 0, v[192:193]
	s_mov_b32 m0, s10
	v_lshl_add_u64 v[214:215], s[78:79], 0, v[160:161]
	global_load_lds_dwordx4 v[212:213], off
	s_add_i32 m0, s10, 0x2000
	v_lshl_add_u64 v[216:217], s[46:47], 0, v[156:157]
	global_load_lds_dwordx4 v[214:215], off
	s_mov_b32 m0, s23
	v_lshl_add_u64 v[218:219], s[46:47], 0, v[158:159]
	global_load_lds_dwordx4 v[216:217], off
	s_mov_b32 m0, s51
	s_nop 0
	global_load_lds_dwordx4 v[218:219], off
	s_waitcnt vmcnt(8)
	s_waitcnt lgkmcnt(0)
	s_setprio 1
	s_barrier
; #define PG8_STAGE(bufoff, gbase, voff) do { _Pragma("unroll") for (int _i = 0; _i < 2; ++_i) \
;         __builtin_amdgcn_global_load_lds((const unsigned*)((const char*)(gbase) + (voff)[_i]), (PG8_LAS unsigned*)(lds + (bufoff) + ldsw + _i * 8192), 16, 0, 0); } while (0)
; #define PG8_LDA(dst, b, h) do { _Pragma("unroll") for (int m = 0; m < 4; ++m) _Pragma("unroll") for (int k = 0; k < 2; ++k) dst[m][k] = *(const PG8_LAS bf16x8*)(lds + PG8_SA(b, h) + aoff + m * 2048 + k * 1024); } while (0)
; #define PG8_LDB(dst, b, h) do { _Pragma("unroll") for (int n = 0; n < 2; ++n) _Pragma("unroll") for (int k = 0; k < 2; ++k) dst[n][k] = *(const PG8_LAS bf16x8*)(lds + PG8_SB(b, h) + boff + n * 2048 + k * 1024); } while (0)
; #define PG8_MMA(ai, bj, At, Bt) do { __builtin_amdgcn_s_setprio(1); _Pragma("unroll") for (int m = 0; m < 4; ++m) _Pragma("unroll") for (int n = 0; n < 2; ++n) _Pragma("unroll") for (int k = 0; k < 2; ++k) \
;         acc[ai][bj][m][n] = __builtin_amdgcn_mfma_f32_16x16x32_bf16(Bt[n][k], At[m][k], acc[ai][bj][m][n], 0, 0, 0); __builtin_amdgcn_s_setprio(0); } while (0)
; #define PG8_WAIT_V(n) asm volatile("s_waitcnt vmcnt(" #n ")" ::: "memory")
; #define PG8_WAIT_L(n) asm volatile("s_waitcnt lgkmcnt(" #n ")" ::: "memory")
; #define PG8_BAR __builtin_amdgcn_s_barrier()
; #define PG8_SCHED __builtin_amdgcn_sched_barrier(0)
; template <class Epi, class Sched, bool ALIGN_EPI = false, bool SP2 = false>
; __device__ __forceinline__ void gemm_phase(PG8_LAS unsigned char* lds, const Gemm g, const Sched& S, const Epi& E) {
;     ...
;             PG8_WAIT_V(8); PG8_WAIT_L(0); PG8_BAR; PG8_MMA(1, 0, At, B0); PG8_MMA(1, 1, At, B1); PG8_BAR; PG8_SCHED;
;             PG8_LDB(B0, 1, 0); PG8_LDB(B1, 1, 1); PG8_SCHED; PG8_LDA(At, 1, 0); PG8_STAGE(PG8_SA(0, 1), a2 + hstep, voffA);
;             PG8_WAIT_V(8); PG8_WAIT_L(0); PG8_BAR; PG8_MMA(0, 0, At, B0); PG8_MMA(0, 1, At, B1); PG8_BAR; PG8_SCHED;
	v_mfma_f32_16x16x32_bf16 v[60:63], v[128:131], v[170:173], v[60:63]
	v_mfma_f32_16x16x32_bf16 v[56:59], v[136:139], v[170:173], v[56:59]
	v_mfma_f32_16x16x32_bf16 v[44:47], v[128:131], v[178:181], v[44:47]
	v_mfma_f32_16x16x32_bf16 v[40:43], v[136:139], v[178:181], v[40:43]
	v_mfma_f32_16x16x32_bf16 v[28:31], v[128:131], v[194:197], v[28:31]
	v_mfma_f32_16x16x32_bf16 v[24:27], v[136:139], v[194:197], v[24:27]
	v_mfma_f32_16x16x32_bf16 v[12:15], v[128:131], v[202:205], v[12:15]
	v_mfma_f32_16x16x32_bf16 v[8:11], v[136:139], v[202:205], v[8:11]
	v_mfma_f32_16x16x32_bf16 v[60:63], v[132:135], v[174:177], v[60:63]
	v_mfma_f32_16x16x32_bf16 v[56:59], v[140:143], v[174:177], v[56:59]
	v_mfma_f32_16x16x32_bf16 v[44:47], v[132:135], v[186:189], v[44:47]
	v_mfma_f32_16x16x32_bf16 v[40:43], v[140:143], v[186:189], v[40:43]
	v_mfma_f32_16x16x32_bf16 v[28:31], v[132:135], v[198:201], v[28:31]
	v_mfma_f32_16x16x32_bf16 v[24:27], v[140:143], v[198:201], v[24:27]
	v_mfma_f32_16x16x32_bf16 v[12:15], v[132:135], v[206:209], v[12:15]
	v_mfma_f32_16x16x32_bf16 v[8:11], v[140:143], v[206:209], v[8:11]
	s_setprio 0
	s_setprio 1
	v_mfma_f32_16x16x32_bf16 v[52:55], v[144:147], v[170:173], v[52:55]
	v_mfma_f32_16x16x32_bf16 v[48:51], v[152:155], v[170:173], v[48:51]
	v_mfma_f32_16x16x32_bf16 v[36:39], v[144:147], v[178:181], v[36:39]
	v_mfma_f32_16x16x32_bf16 v[32:35], v[152:155], v[178:181], v[32:35]
	v_mfma_f32_16x16x32_bf16 v[20:23], v[144:147], v[194:197], v[20:23]
	v_mfma_f32_16x16x32_bf16 v[16:19], v[152:155], v[194:197], v[16:19]
	v_mfma_f32_16x16x32_bf16 v[4:7], v[144:147], v[202:205], v[4:7]
	v_mfma_f32_16x16x32_bf16 v[0:3], v[152:155], v[202:205], v[0:3]
	v_mfma_f32_16x16x32_bf16 v[52:55], v[148:151], v[174:177], v[52:55]
	v_mfma_f32_16x16x32_bf16 v[48:51], v[166:169], v[174:177], v[48:51]
	v_mfma_f32_16x16x32_bf16 v[36:39], v[148:151], v[186:189], v[36:39]
	v_mfma_f32_16x16x32_bf16 v[32:35], v[166:169], v[186:189], v[32:35]
	v_mfma_f32_16x16x32_bf16 v[20:23], v[148:151], v[198:201], v[20:23]
	v_mfma_f32_16x16x32_bf16 v[16:19], v[166:169], v[198:201], v[16:19]
	v_mfma_f32_16x16x32_bf16 v[4:7], v[148:151], v[206:209], v[4:7]
	v_mfma_f32_16x16x32_bf16 v[0:3], v[166:169], v[206:209], v[0:3]
	s_barrier
	s_setprio 0
	s_add_i32 s10, 0, 0x18000
	s_add_i32 s11, 0, 0x1c000
	v_add_u32_e32 v140, s10, v183
	v_add_u32_e32 v166, s11, v183
	ds_read_b128 v[128:131], v140
	ds_read_b128 v[132:135], v140 offset:1024
	ds_read_b128 v[136:139], v140 offset:2048
	ds_read_b128 v[140:143], v140 offset:3072
	ds_read_b128 v[144:147], v166
	ds_read_b128 v[148:151], v166 offset:1024
	ds_read_b128 v[152:155], v166 offset:2048
	ds_read_b128 v[166:169], v166 offset:3072
	s_add_u32 s46, s46, s52
	s_addc_u32 s47, s47, 0
	s_mov_b32 m0, s68
	v_lshl_add_u64 v[220:221], s[46:47], 0, v[156:157]
	ds_read_b128 v[170:173], v185 offset:32768
	ds_read_b128 v[174:177], v185 offset:33792
	ds_read_b128 v[178:181], v185 offset:34816
	ds_read_b128 v[186:189], v185 offset:35840
	ds_read_b128 v[194:197], v185 offset:36864
	ds_read_b128 v[198:201], v185 offset:37888
	ds_read_b128 v[202:205], v185 offset:38912
	ds_read_b128 v[206:209], v185 offset:39936
	global_load_lds_dwordx4 v[220:221], off
	v_lshl_add_u64 v[220:221], s[46:47], 0, v[158:159]
	s_mov_b32 m0, s69
	s_nop 0
	global_load_lds_dwordx4 v[220:221], off
	s_waitcnt vmcnt(8)
	s_waitcnt lgkmcnt(0)
	s_setprio 1
	s_barrier
	v_mfma_f32_16x16x32_bf16 v[124:127], v[128:131], v[170:173], v[124:127]
	v_mfma_f32_16x16x32_bf16 v[120:123], v[136:139], v[170:173], v[120:123]
	v_mfma_f32_16x16x32_bf16 v[108:111], v[128:131], v[178:181], v[108:111]
	v_mfma_f32_16x16x32_bf16 v[104:107], v[136:139], v[178:181], v[104:107]
	v_mfma_f32_16x16x32_bf16 v[92:95], v[128:131], v[194:197], v[92:95]
	v_mfma_f32_16x16x32_bf16 v[88:91], v[136:139], v[194:197], v[88:91]
	v_mfma_f32_16x16x32_bf16 v[76:79], v[128:131], v[202:205], v[76:79]
	v_mfma_f32_16x16x32_bf16 v[72:75], v[136:139], v[202:205], v[72:75]
	v_mfma_f32_16x16x32_bf16 v[124:127], v[132:135], v[174:177], v[124:127]
	v_mfma_f32_16x16x32_bf16 v[120:123], v[140:143], v[174:177], v[120:123]
	v_mfma_f32_16x16x32_bf16 v[108:111], v[132:135], v[186:189], v[108:111]
	v_mfma_f32_16x16x32_bf16 v[104:107], v[140:143], v[186:189], v[104:107]
	v_mfma_f32_16x16x32_bf16 v[92:95], v[132:135], v[198:201], v[92:95]
	v_mfma_f32_16x16x32_bf16 v[88:91], v[140:143], v[198:201], v[88:91]
	v_mfma_f32_16x16x32_bf16 v[76:79], v[132:135], v[206:209], v[76:79]
	v_mfma_f32_16x16x32_bf16 v[72:75], v[140:143], v[206:209], v[72:75]
	s_setprio 0
	s_setprio 1
	v_mfma_f32_16x16x32_bf16 v[116:119], v[144:147], v[170:173], v[116:119]
	v_mfma_f32_16x16x32_bf16 v[112:115], v[152:155], v[170:173], v[112:115]
	v_mfma_f32_16x16x32_bf16 v[100:103], v[144:147], v[178:181], v[100:103]
	v_mfma_f32_16x16x32_bf16 v[96:99], v[152:155], v[178:181], v[96:99]
	v_mfma_f32_16x16x32_bf16 v[84:87], v[144:147], v[194:197], v[84:87]
	v_mfma_f32_16x16x32_bf16 v[80:83], v[152:155], v[194:197], v[80:83]
	v_mfma_f32_16x16x32_bf16 v[68:71], v[144:147], v[202:205], v[68:71]
	v_mfma_f32_16x16x32_bf16 v[64:67], v[152:155], v[202:205], v[64:67]
	v_mfma_f32_16x16x32_bf16 v[116:119], v[148:151], v[174:177], v[116:119]
	v_mfma_f32_16x16x32_bf16 v[112:115], v[166:169], v[174:177], v[112:115]
	v_mfma_f32_16x16x32_bf16 v[100:103], v[148:151], v[186:189], v[100:103]
	v_mfma_f32_16x16x32_bf16 v[96:99], v[166:169], v[186:189], v[96:99]
	v_mfma_f32_16x16x32_bf16 v[84:87], v[148:151], v[198:201], v[84:87]
	v_mfma_f32_16x16x32_bf16 v[80:83], v[166:169], v[198:201], v[80:83]
	v_mfma_f32_16x16x32_bf16 v[68:71], v[148:151], v[206:209], v[68:71]
	v_mfma_f32_16x16x32_bf16 v[64:67], v[166:169], v[206:209], v[64:67]
	s_barrier
; #define PG8_STAGE(bufoff, gbase, voff) do { _Pragma("unroll") for (int _i = 0; _i < 2; ++_i) \
;         __builtin_amdgcn_global_load_lds((const unsigned*)((const char*)(gbase) + (voff)[_i]), (PG8_LAS unsigned*)(lds + (bufoff) + ldsw + _i * 8192), 16, 0, 0); } while (0)
; #define PG8_LDA(dst, b, h) do { _Pragma("unroll") for (int m = 0; m < 4; ++m) _Pragma("unroll") for (int k = 0; k < 2; ++k) dst[m][k] = *(const PG8_LAS bf16x8*)(lds + PG8_SA(b, h) + aoff + m * 2048 + k * 1024); } while (0)
; #define PG8_MMA(ai, bj, At, Bt) do { __builtin_amdgcn_s_setprio(1); _Pragma("unroll") for (int m = 0; m < 4; ++m) _Pragma("unroll") for (int n = 0; n < 2; ++n) _Pragma("unroll") for (int k = 0; k < 2; ++k) \
;         acc[ai][bj][m][n] = __builtin_amdgcn_mfma_f32_16x16x32_bf16(Bt[n][k], At[m][k], acc[ai][bj][m][n], 0, 0, 0); __builtin_amdgcn_s_setprio(0); } while (0)
; #define PG8_WAIT_V(n) asm volatile("s_waitcnt vmcnt(" #n ")" ::: "memory")
; #define PG8_WAIT_L(n) asm volatile("s_waitcnt lgkmcnt(" #n ")" ::: "memory")
; #define PG8_BAR __builtin_amdgcn_s_barrier()
; #define PG8_SCHED __builtin_amdgcn_sched_barrier(0)
; template <class Epi, class Sched, bool ALIGN_EPI = false, bool SP2 = false>
; __device__ __forceinline__ void gemm_phase(PG8_LAS unsigned char* lds, const Gemm g, const Sched& S, const Epi& E) {
;     ...
;         for (int t = 0; t < nt; t += 2) {
;             const bool last = (t == nt - 2);
;             const char* a1 = cA + (size_t)(t + 1) * kstep;
;     ...
;             PG8_LDA(At, 1, 1); PG8_STAGE(PG8_SB(1, 0), b3, voffB); PG8_STAGE(PG8_SB(1, 1), b3 + hstep, voffB); PG8_STAGE(PG8_SA(1, 0), a3, voffA);
;             PG8_WAIT_V(8); PG8_WAIT_L(0); PG8_BAR; PG8_MMA(1, 0, At, B0); PG8_MMA(1, 1, At, B1); PG8_BAR; PG8_SCHED;
	s_setprio 0
	s_add_i32 s10, s10, s22
	v_lshl_add_u64 v[190:191], v[190:191], 0, s[36:37]
	s_mov_b32 m0, s10
	ds_read_b128 v[170:173], v185 offset:49152
	ds_read_b128 v[174:177], v185 offset:50176
	ds_read_b128 v[178:181], v185 offset:51200
	ds_read_b128 v[186:189], v185 offset:52224
	ds_read_b128 v[194:197], v185 offset:53248
	ds_read_b128 v[198:201], v185 offset:54272
	ds_read_b128 v[202:205], v185 offset:55296
	ds_read_b128 v[206:209], v185 offset:56320
	global_load_lds_dwordx4 v[190:191], off
	v_lshl_add_u64 v[190:191], v[210:211], 0, s[36:37]
	s_add_i32 m0, s10, 0x2000
	s_add_i32 s10, s11, s22
	global_load_lds_dwordx4 v[190:191], off
	v_lshl_add_u64 v[190:191], v[212:213], 0, s[36:37]
	s_mov_b32 m0, s10
	s_nop 0
	global_load_lds_dwordx4 v[190:191], off
	v_lshl_add_u64 v[190:191], v[214:215], 0, s[36:37]
	s_add_i32 m0, s10, 0x2000
	s_nop 0
	global_load_lds_dwordx4 v[190:191], off
	v_lshl_add_u64 v[190:191], v[216:217], 0, s[36:37]
	s_mov_b32 m0, s70
	s_nop 0
	global_load_lds_dwordx4 v[190:191], off
	v_lshl_add_u64 v[190:191], v[218:219], 0, s[36:37]
	s_mov_b32 m0, s71
	s_nop 0
	global_load_lds_dwordx4 v[190:191], off
	s_waitcnt vmcnt(8)
	s_waitcnt lgkmcnt(0)
	s_setprio 1
	s_barrier
	v_mfma_f32_16x16x32_bf16 v[60:63], v[128:131], v[170:173], v[60:63]
	v_mfma_f32_16x16x32_bf16 v[56:59], v[136:139], v[170:173], v[56:59]
	v_mfma_f32_16x16x32_bf16 v[44:47], v[128:131], v[178:181], v[44:47]
	v_mfma_f32_16x16x32_bf16 v[40:43], v[136:139], v[178:181], v[40:43]
	v_mfma_f32_16x16x32_bf16 v[28:31], v[128:131], v[194:197], v[28:31]
	v_mfma_f32_16x16x32_bf16 v[24:27], v[136:139], v[194:197], v[24:27]
	v_mfma_f32_16x16x32_bf16 v[12:15], v[128:131], v[202:205], v[12:15]
	v_mfma_f32_16x16x32_bf16 v[8:11], v[136:139], v[202:205], v[8:11]
	v_mfma_f32_16x16x32_bf16 v[60:63], v[132:135], v[174:177], v[60:63]
	v_mfma_f32_16x16x32_bf16 v[56:59], v[140:143], v[174:177], v[56:59]
	v_mfma_f32_16x16x32_bf16 v[44:47], v[132:135], v[186:189], v[44:47]
	v_mfma_f32_16x16x32_bf16 v[40:43], v[140:143], v[186:189], v[40:43]
	v_mfma_f32_16x16x32_bf16 v[28:31], v[132:135], v[198:201], v[28:31]
	v_mfma_f32_16x16x32_bf16 v[24:27], v[140:143], v[198:201], v[24:27]
	v_mfma_f32_16x16x32_bf16 v[12:15], v[132:135], v[206:209], v[12:15]
	v_mfma_f32_16x16x32_bf16 v[8:11], v[140:143], v[206:209], v[8:11]
	s_setprio 0
	s_setprio 1
	v_mfma_f32_16x16x32_bf16 v[52:55], v[144:147], v[170:173], v[52:55]
	v_mfma_f32_16x16x32_bf16 v[48:51], v[152:155], v[170:173], v[48:51]
	v_mfma_f32_16x16x32_bf16 v[36:39], v[144:147], v[178:181], v[36:39]
	v_mfma_f32_16x16x32_bf16 v[32:35], v[152:155], v[178:181], v[32:35]
	v_mfma_f32_16x16x32_bf16 v[20:23], v[144:147], v[194:197], v[20:23]
	v_mfma_f32_16x16x32_bf16 v[16:19], v[152:155], v[194:197], v[16:19]
	v_mfma_f32_16x16x32_bf16 v[4:7], v[144:147], v[202:205], v[4:7]
	v_mfma_f32_16x16x32_bf16 v[0:3], v[152:155], v[202:205], v[0:3]
	v_mfma_f32_16x16x32_bf16 v[52:55], v[148:151], v[174:177], v[52:55]
	v_mfma_f32_16x16x32_bf16 v[48:51], v[166:169], v[174:177], v[48:51]
	v_mfma_f32_16x16x32_bf16 v[36:39], v[148:151], v[186:189], v[36:39]
	v_mfma_f32_16x16x32_bf16 v[32:35], v[166:169], v[186:189], v[32:35]
	v_mfma_f32_16x16x32_bf16 v[20:23], v[148:151], v[198:201], v[20:23]
	v_mfma_f32_16x16x32_bf16 v[16:19], v[166:169], v[198:201], v[16:19]
	v_mfma_f32_16x16x32_bf16 v[4:7], v[148:151], v[206:209], v[4:7]
	v_mfma_f32_16x16x32_bf16 v[0:3], v[166:169], v[206:209], v[0:3]
	s_barrier
	s_setprio 0
	s_add_u32 s44, s44, 0x100
	s_addc_u32 s45, s45, 0
	s_add_u32 s19, s19, 0x100
	s_addc_u32 s20, s20, 0
	s_cmp_ge_u32 s66, s73
	s_mov_b32 s46, s66
	s_cbranch_scc0 .LBB0_63
	s_and_b64 vcc, exec, s[56:57]
	s_cbranch_vccz .LBB0_66
	s_barrier

; #define PG8_STAGE(bufoff, gbase, voff) do { _Pragma("unroll") for (int _i = 0; _i < 2; ++_i) \
;         __builtin_amdgcn_global_load_lds((const unsigned*)((const char*)(gbase) + (voff)[_i]), (PG8_LAS unsigned*)(lds + (bufoff) + ldsw + _i * 8192), 16, 0, 0); } while (0)
; #define PG8_LDA(dst, b, h) do { _Pragma("unroll") for (int m = 0; m < 4; ++m) _Pragma("unroll") for (int k = 0; k < 2; ++k) dst[m][k] = *(const PG8_LAS bf16x8*)(lds + PG8_SA(b, h) + aoff + m * 2048 + k * 1024); } while (0)
; #define PG8_LDB(dst, b, h) do { _Pragma("unroll") for (int n = 0; n < 2; ++n) _Pragma("unroll") for (int k = 0; k < 2; ++k) dst[n][k] = *(const PG8_LAS bf16x8*)(lds + PG8_SB(b, h) + boff + n * 2048 + k * 1024); } while (0)
; #define PG8_MMA(ai, bj, At, Bt) do { __builtin_amdgcn_s_setprio(1); _Pragma("unroll") for (int m = 0; m < 4; ++m) _Pragma("unroll") for (int n = 0; n < 2; ++n) _Pragma("unroll") for (int k = 0; k < 2; ++k) \
;         acc[ai][bj][m][n] = __builtin_amdgcn_mfma_f32_16x16x32_bf16(Bt[n][k], At[m][k], acc[ai][bj][m][n], 0, 0, 0); __builtin_amdgcn_s_setprio(0); } while (0)
; #define PG8_WAIT_V(n) asm volatile("s_waitcnt vmcnt(" #n ")" ::: "memory")
; #define PG8_WAIT_L(n) asm volatile("s_waitcnt lgkmcnt(" #n ")" ::: "memory")
; template <class Epi, class Sched, bool ALIGN_EPI = false, bool SP2 = false>
; __device__ __forceinline__ void gemm_phase(PG8_LAS unsigned char* lds, const Gemm g, const Sched& S, const Epi& E) {
;     ...
;             const bool last = (t == nt - 2);
;             const char* a1 = cA + (size_t)(t + 1) * kstep;
;             const char* a2 = last ? nA : cA + (size_t)(t + 2) * kstep; const char* b2 = last ? nB : cB + (size_t)(t + 2) * kstep;
;             const char* a3 = a2 + kstep; const char* b3 = b2 + kstep;
;             if (last && has_next) S.a_ready(nxt);
;             if constexpr (SP2) {
;             PG8_LDB(B0, 0, 0); PG8_LDB(B1, 0, 1); PG8_SCHED; PG8_LDA(At, 0, 0); PG8_STAGE(PG8_SA(1, 1), a1 + hstep, voffA);
;             PG8_WAIT_V(8); PG8_WAIT_L(0); PG8_BAR; PG8_MMA(0, 0, At, B0); PG8_MMA(0, 1, At, B1); PG8_BAR; PG8_SCHED;
;             PG8_LDA(At, 0, 1); PG8_STAGE(PG8_SB(0, 0), b2, voffB); PG8_STAGE(PG8_SB(0, 1), b2 + hstep, voffB); PG8_STAGE(PG8_SA(0, 0), a2, voffA);
;             PG8_WAIT_V(8); PG8_WAIT_L(0); PG8_BAR; PG8_MMA(1, 0, At, B0); PG8_MMA(1, 1, At, B1); PG8_BAR; PG8_SCHED;
.LBB0_200:
	s_add_u32 s10, s56, 0xfffc0080
	s_addc_u32 s11, s57, -1
	s_add_i32 s77, 0, 0x10000
	s_cmp_eq_u32 s76, 12
	s_cselect_b32 s61, s18, s11
	s_cselect_b32 s60, s19, s10
	s_cselect_b32 s59, s20, s51
	s_cselect_b32 s58, s43, s49
	s_add_i32 s10, 0, 0x14000
	v_add_u32_e32 v140, s77, v163
	v_add_u32_e32 v162, s10, v163
	ds_read_b128 v[128:131], v140
	ds_read_b128 v[132:135], v140 offset:1024
	ds_read_b128 v[136:139], v140 offset:2048
	ds_read_b128 v[140:143], v140 offset:3072
	ds_read_b128 v[166:169], v162
	ds_read_b128 v[170:173], v162 offset:1024
	ds_read_b128 v[174:177], v162 offset:2048
	ds_read_b128 v[178:181], v162 offset:3072
	v_lshl_add_u64 v[190:191], s[56:57], 0, v[158:159]
	s_add_i32 m0, s64, 0xc000
	ds_read_b128 v[182:185], v165
	ds_read_b128 v[186:189], v165 offset:1024
	ds_read_b128 v[194:197], v165 offset:2048
	ds_read_b128 v[198:201], v165 offset:3072
	ds_read_b128 v[202:205], v165 offset:4096
	ds_read_b128 v[206:209], v165 offset:5120
	ds_read_b128 v[210:213], v165 offset:6144
	ds_read_b128 v[214:217], v165 offset:7168
	global_load_lds_dwordx4 v[190:191], off
	v_lshl_add_u64 v[190:191], s[56:57], 0, v[160:161]
	s_add_i32 m0, s64, 0xe000
	s_nop 0
	global_load_lds_dwordx4 v[190:191], off
	s_waitcnt vmcnt(8)
	s_waitcnt lgkmcnt(0)
	s_setprio 1
	s_barrier
	v_mfma_f32_16x16x32_bf16 v[124:127], v[128:131], v[182:185], v[124:127]
	v_mfma_f32_16x16x32_bf16 v[120:123], v[136:139], v[182:185], v[120:123]
	v_mfma_f32_16x16x32_bf16 v[112:115], v[128:131], v[194:197], v[112:115]
	v_mfma_f32_16x16x32_bf16 v[104:107], v[136:139], v[194:197], v[104:107]
	v_mfma_f32_16x16x32_bf16 v[96:99], v[128:131], v[202:205], v[96:99]
	v_mfma_f32_16x16x32_bf16 v[88:91], v[136:139], v[202:205], v[88:91]
	v_mfma_f32_16x16x32_bf16 v[80:83], v[128:131], v[210:213], v[80:83]
	v_mfma_f32_16x16x32_bf16 v[72:75], v[136:139], v[210:213], v[72:75]
	v_mfma_f32_16x16x32_bf16 v[124:127], v[132:135], v[186:189], v[124:127]
	v_mfma_f32_16x16x32_bf16 v[120:123], v[140:143], v[186:189], v[120:123]
	v_mfma_f32_16x16x32_bf16 v[112:115], v[132:135], v[198:201], v[112:115]
	v_mfma_f32_16x16x32_bf16 v[104:107], v[140:143], v[198:201], v[104:107]
	v_mfma_f32_16x16x32_bf16 v[96:99], v[132:135], v[206:209], v[96:99]
	v_mfma_f32_16x16x32_bf16 v[88:91], v[140:143], v[206:209], v[88:91]
	v_mfma_f32_16x16x32_bf16 v[80:83], v[132:135], v[214:217], v[80:83]
	v_mfma_f32_16x16x32_bf16 v[72:75], v[140:143], v[214:217], v[72:75]
	s_setprio 0
	s_setprio 1
	v_mfma_f32_16x16x32_bf16 v[116:119], v[166:169], v[182:185], v[116:119]
	v_mfma_f32_16x16x32_bf16 v[108:111], v[174:177], v[182:185], v[108:111]
	v_mfma_f32_16x16x32_bf16 v[100:103], v[166:169], v[194:197], v[100:103]
	v_mfma_f32_16x16x32_bf16 v[92:95], v[174:177], v[194:197], v[92:95]
	v_mfma_f32_16x16x32_bf16 v[84:87], v[166:169], v[202:205], v[84:87]
	v_mfma_f32_16x16x32_bf16 v[76:79], v[174:177], v[202:205], v[76:79]
	v_mfma_f32_16x16x32_bf16 v[68:71], v[166:169], v[210:213], v[68:71]
	v_mfma_f32_16x16x32_bf16 v[64:67], v[174:177], v[210:213], v[64:67]
	v_mfma_f32_16x16x32_bf16 v[116:119], v[170:173], v[186:189], v[116:119]
	v_mfma_f32_16x16x32_bf16 v[108:111], v[178:181], v[186:189], v[108:111]
	v_mfma_f32_16x16x32_bf16 v[100:103], v[170:173], v[198:201], v[100:103]
	v_mfma_f32_16x16x32_bf16 v[92:95], v[178:181], v[198:201], v[92:95]
	v_mfma_f32_16x16x32_bf16 v[84:87], v[170:173], v[206:209], v[84:87]
	v_mfma_f32_16x16x32_bf16 v[76:79], v[178:181], v[206:209], v[76:79]
	v_mfma_f32_16x16x32_bf16 v[68:71], v[170:173], v[214:217], v[68:71]
	v_mfma_f32_16x16x32_bf16 v[64:67], v[178:181], v[214:217], v[64:67]
	s_barrier
	s_setprio 0
	s_add_i32 s11, s77, s63
	v_lshl_add_u64 v[190:191], s[58:59], 0, v[146:147]
	s_mov_b32 m0, s11
	ds_read_b128 v[182:185], v165 offset:16384
	ds_read_b128 v[186:189], v165 offset:17408
	ds_read_b128 v[194:197], v165 offset:18432
	ds_read_b128 v[198:201], v165 offset:19456
	ds_read_b128 v[202:205], v165 offset:20480
	ds_read_b128 v[206:209], v165 offset:21504
	ds_read_b128 v[210:213], v165 offset:22528
	ds_read_b128 v[214:217], v165 offset:23552
	global_load_lds_dwordx4 v[190:191], off
	s_add_i32 m0, s11, 0x2000
	s_add_u32 s78, s58, 0x40000
	v_lshl_add_u64 v[218:219], s[58:59], 0, v[150:151]
	s_addc_u32 s79, s59, 0
	s_add_i32 s10, s10, s63
	global_load_lds_dwordx4 v[218:219], off
	v_lshl_add_u64 v[220:221], s[78:79], 0, v[146:147]
	s_mov_b32 m0, s10
	v_lshl_add_u64 v[222:223], s[60:61], 0, v[148:149]
	global_load_lds_dwordx4 v[220:221], off
	v_lshl_add_u64 v[220:221], s[78:79], 0, v[150:151]
	s_add_i32 m0, s10, 0x2000
	s_nop 0
	global_load_lds_dwordx4 v[220:221], off
	v_lshl_add_u64 v[220:221], s[60:61], 0, v[144:145]
	s_mov_b32 m0, s64
	s_nop 0
	global_load_lds_dwordx4 v[220:221], off
	s_mov_b32 m0, s65
	s_nop 0
	global_load_lds_dwordx4 v[222:223], off
	s_waitcnt vmcnt(8)
	s_waitcnt lgkmcnt(0)
	s_setprio 1
	s_barrier
; #define PG8_STAGE(bufoff, gbase, voff) do { _Pragma("unroll") for (int _i = 0; _i < 2; ++_i) \
;         __builtin_amdgcn_global_load_lds((const unsigned*)((const char*)(gbase) + (voff)[_i]), (PG8_LAS unsigned*)(lds + (bufoff) + ldsw + _i * 8192), 16, 0, 0); } while (0)
; #define PG8_LDA(dst, b, h) do { _Pragma("unroll") for (int m = 0; m < 4; ++m) _Pragma("unroll") for (int k = 0; k < 2; ++k) dst[m][k] = *(const PG8_LAS bf16x8*)(lds + PG8_SA(b, h) + aoff + m * 2048 + k * 1024); } while (0)
; #define PG8_LDB(dst, b, h) do { _Pragma("unroll") for (int n = 0; n < 2; ++n) _Pragma("unroll") for (int k = 0; k < 2; ++k) dst[n][k] = *(const PG8_LAS bf16x8*)(lds + PG8_SB(b, h) + boff + n * 2048 + k * 1024); } while (0)
; #define PG8_MMA(ai, bj, At, Bt) do { __builtin_amdgcn_s_setprio(1); _Pragma("unroll") for (int m = 0; m < 4; ++m) _Pragma("unroll") for (int n = 0; n < 2; ++n) _Pragma("unroll") for (int k = 0; k < 2; ++k) \
;         acc[ai][bj][m][n] = __builtin_amdgcn_mfma_f32_16x16x32_bf16(Bt[n][k], At[m][k], acc[ai][bj][m][n], 0, 0, 0); __builtin_amdgcn_s_setprio(0); } while (0)
; #define PG8_WAIT_V(n) asm volatile("s_waitcnt vmcnt(" #n ")" ::: "memory")
; #define PG8_WAIT_L(n) asm volatile("s_waitcnt lgkmcnt(" #n ")" ::: "memory")
; #define PG8_BAR __builtin_amdgcn_s_barrier()
; #define PG8_SCHED __builtin_amdgcn_sched_barrier(0)
; template <class Epi, class Sched, bool ALIGN_EPI = false, bool SP2 = false>
; __device__ __forceinline__ void gemm_phase(PG8_LAS unsigned char* lds, const Gemm g, const Sched& S, const Epi& E) {
;     ...
;             PG8_WAIT_V(8); PG8_WAIT_L(0); PG8_BAR; PG8_MMA(1, 0, At, B0); PG8_MMA(1, 1, At, B1); PG8_BAR; PG8_SCHED;
;             PG8_LDB(B0, 1, 0); PG8_LDB(B1, 1, 1); PG8_SCHED; PG8_LDA(At, 1, 0); PG8_STAGE(PG8_SA(0, 1), a2 + hstep, voffA);
;             PG8_WAIT_V(8); PG8_WAIT_L(0); PG8_BAR; PG8_MMA(0, 0, At, B0); PG8_MMA(0, 1, At, B1); PG8_BAR; PG8_SCHED;
	v_mfma_f32_16x16x32_bf16 v[60:63], v[128:131], v[182:185], v[60:63]
	v_mfma_f32_16x16x32_bf16 v[56:59], v[136:139], v[182:185], v[56:59]
	v_mfma_f32_16x16x32_bf16 v[48:51], v[128:131], v[194:197], v[48:51]
	v_mfma_f32_16x16x32_bf16 v[40:43], v[136:139], v[194:197], v[40:43]
	v_mfma_f32_16x16x32_bf16 v[32:35], v[128:131], v[202:205], v[32:35]
	v_mfma_f32_16x16x32_bf16 v[24:27], v[136:139], v[202:205], v[24:27]
	v_mfma_f32_16x16x32_bf16 v[16:19], v[128:131], v[210:213], v[16:19]
	v_mfma_f32_16x16x32_bf16 v[8:11], v[136:139], v[210:213], v[8:11]
	v_mfma_f32_16x16x32_bf16 v[60:63], v[132:135], v[186:189], v[60:63]
	v_mfma_f32_16x16x32_bf16 v[56:59], v[140:143], v[186:189], v[56:59]
	v_mfma_f32_16x16x32_bf16 v[48:51], v[132:135], v[198:201], v[48:51]
	v_mfma_f32_16x16x32_bf16 v[40:43], v[140:143], v[198:201], v[40:43]
	v_mfma_f32_16x16x32_bf16 v[32:35], v[132:135], v[206:209], v[32:35]
	v_mfma_f32_16x16x32_bf16 v[24:27], v[140:143], v[206:209], v[24:27]
	v_mfma_f32_16x16x32_bf16 v[16:19], v[132:135], v[214:217], v[16:19]
	v_mfma_f32_16x16x32_bf16 v[8:11], v[140:143], v[214:217], v[8:11]
	s_setprio 0
	s_setprio 1
	v_mfma_f32_16x16x32_bf16 v[52:55], v[166:169], v[182:185], v[52:55]
	v_mfma_f32_16x16x32_bf16 v[44:47], v[174:177], v[182:185], v[44:47]
	v_mfma_f32_16x16x32_bf16 v[36:39], v[166:169], v[194:197], v[36:39]
	v_mfma_f32_16x16x32_bf16 v[28:31], v[174:177], v[194:197], v[28:31]
	v_mfma_f32_16x16x32_bf16 v[20:23], v[166:169], v[202:205], v[20:23]
	v_mfma_f32_16x16x32_bf16 v[12:15], v[174:177], v[202:205], v[12:15]
	v_mfma_f32_16x16x32_bf16 v[4:7], v[166:169], v[210:213], v[4:7]
	v_mfma_f32_16x16x32_bf16 v[0:3], v[174:177], v[210:213], v[0:3]
	v_mfma_f32_16x16x32_bf16 v[52:55], v[170:173], v[186:189], v[52:55]
	v_mfma_f32_16x16x32_bf16 v[44:47], v[178:181], v[186:189], v[44:47]
	v_mfma_f32_16x16x32_bf16 v[36:39], v[170:173], v[198:201], v[36:39]
	v_mfma_f32_16x16x32_bf16 v[28:31], v[178:181], v[198:201], v[28:31]
	v_mfma_f32_16x16x32_bf16 v[20:23], v[170:173], v[206:209], v[20:23]
	v_mfma_f32_16x16x32_bf16 v[12:15], v[178:181], v[206:209], v[12:15]
	v_mfma_f32_16x16x32_bf16 v[4:7], v[170:173], v[214:217], v[4:7]
	v_mfma_f32_16x16x32_bf16 v[0:3], v[178:181], v[214:217], v[0:3]
	s_barrier
	s_setprio 0
	s_add_i32 s10, 0, 0x18000
	s_add_i32 s11, 0, 0x1c000
	v_add_u32_e32 v140, s10, v163
	v_add_u32_e32 v162, s11, v163
	ds_read_b128 v[128:131], v140
	ds_read_b128 v[132:135], v140 offset:1024
	ds_read_b128 v[136:139], v140 offset:2048
	ds_read_b128 v[140:143], v140 offset:3072
	ds_read_b128 v[166:169], v162
	ds_read_b128 v[170:173], v162 offset:1024
	ds_read_b128 v[174:177], v162 offset:2048
	ds_read_b128 v[178:181], v162 offset:3072
	s_add_u32 s60, s60, 0x40000
	s_addc_u32 s61, s61, 0
	s_mov_b32 m0, s66
	v_lshl_add_u64 v[224:225], s[60:61], 0, v[144:145]
	ds_read_b128 v[182:185], v165 offset:32768
	ds_read_b128 v[186:189], v165 offset:33792
	ds_read_b128 v[194:197], v165 offset:34816
	ds_read_b128 v[198:201], v165 offset:35840
	ds_read_b128 v[202:205], v165 offset:36864
	ds_read_b128 v[206:209], v165 offset:37888
	ds_read_b128 v[210:213], v165 offset:38912
	ds_read_b128 v[214:217], v165 offset:39936
	global_load_lds_dwordx4 v[224:225], off
	v_lshl_add_u64 v[224:225], s[60:61], 0, v[148:149]
	s_mov_b32 m0, s67
	s_nop 0
	global_load_lds_dwordx4 v[224:225], off
	s_waitcnt vmcnt(8)
	s_waitcnt lgkmcnt(0)
	s_setprio 1
	s_barrier
	v_mfma_f32_16x16x32_bf16 v[124:127], v[128:131], v[182:185], v[124:127]
	v_mfma_f32_16x16x32_bf16 v[120:123], v[136:139], v[182:185], v[120:123]
	v_mfma_f32_16x16x32_bf16 v[112:115], v[128:131], v[194:197], v[112:115]
	v_mfma_f32_16x16x32_bf16 v[104:107], v[136:139], v[194:197], v[104:107]
	v_mfma_f32_16x16x32_bf16 v[96:99], v[128:131], v[202:205], v[96:99]
	v_mfma_f32_16x16x32_bf16 v[88:91], v[136:139], v[202:205], v[88:91]
	v_mfma_f32_16x16x32_bf16 v[80:83], v[128:131], v[210:213], v[80:83]
	v_mfma_f32_16x16x32_bf16 v[72:75], v[136:139], v[210:213], v[72:75]
	v_mfma_f32_16x16x32_bf16 v[124:127], v[132:135], v[186:189], v[124:127]
	v_mfma_f32_16x16x32_bf16 v[120:123], v[140:143], v[186:189], v[120:123]
	v_mfma_f32_16x16x32_bf16 v[112:115], v[132:135], v[198:201], v[112:115]
	v_mfma_f32_16x16x32_bf16 v[104:107], v[140:143], v[198:201], v[104:107]
	v_mfma_f32_16x16x32_bf16 v[96:99], v[132:135], v[206:209], v[96:99]
	v_mfma_f32_16x16x32_bf16 v[88:91], v[140:143], v[206:209], v[88:91]
	v_mfma_f32_16x16x32_bf16 v[80:83], v[132:135], v[214:217], v[80:83]
	v_mfma_f32_16x16x32_bf16 v[72:75], v[140:143], v[214:217], v[72:75]
	s_setprio 0
	s_setprio 1
	v_mfma_f32_16x16x32_bf16 v[116:119], v[166:169], v[182:185], v[116:119]
	v_mfma_f32_16x16x32_bf16 v[108:111], v[174:177], v[182:185], v[108:111]
	v_mfma_f32_16x16x32_bf16 v[100:103], v[166:169], v[194:197], v[100:103]
	v_mfma_f32_16x16x32_bf16 v[92:95], v[174:177], v[194:197], v[92:95]
	v_mfma_f32_16x16x32_bf16 v[84:87], v[166:169], v[202:205], v[84:87]
	v_mfma_f32_16x16x32_bf16 v[76:79], v[174:177], v[202:205], v[76:79]
	v_mfma_f32_16x16x32_bf16 v[68:71], v[166:169], v[210:213], v[68:71]
	v_mfma_f32_16x16x32_bf16 v[64:67], v[174:177], v[210:213], v[64:67]
	v_mfma_f32_16x16x32_bf16 v[116:119], v[170:173], v[186:189], v[116:119]
	v_mfma_f32_16x16x32_bf16 v[108:111], v[178:181], v[186:189], v[108:111]
	v_mfma_f32_16x16x32_bf16 v[100:103], v[170:173], v[198:201], v[100:103]
	v_mfma_f32_16x16x32_bf16 v[92:95], v[178:181], v[198:201], v[92:95]
	v_mfma_f32_16x16x32_bf16 v[84:87], v[170:173], v[206:209], v[84:87]
	v_mfma_f32_16x16x32_bf16 v[76:79], v[178:181], v[206:209], v[76:79]
	v_mfma_f32_16x16x32_bf16 v[68:71], v[170:173], v[214:217], v[68:71]
	v_mfma_f32_16x16x32_bf16 v[64:67], v[178:181], v[214:217], v[64:67]
	s_barrier
; #define PG8_STAGE(bufoff, gbase, voff) do { _Pragma("unroll") for (int _i = 0; _i < 2; ++_i) \
;         __builtin_amdgcn_global_load_lds((const unsigned*)((const char*)(gbase) + (voff)[_i]), (PG8_LAS unsigned*)(lds + (bufoff) + ldsw + _i * 8192), 16, 0, 0); } while (0)
; #define PG8_LDA(dst, b, h) do { _Pragma("unroll") for (int m = 0; m < 4; ++m) _Pragma("unroll") for (int k = 0; k < 2; ++k) dst[m][k] = *(const PG8_LAS bf16x8*)(lds + PG8_SA(b, h) + aoff + m * 2048 + k * 1024); } while (0)
; #define PG8_MMA(ai, bj, At, Bt) do { __builtin_amdgcn_s_setprio(1); _Pragma("unroll") for (int m = 0; m < 4; ++m) _Pragma("unroll") for (int n = 0; n < 2; ++n) _Pragma("unroll") for (int k = 0; k < 2; ++k) \
;         acc[ai][bj][m][n] = __builtin_amdgcn_mfma_f32_16x16x32_bf16(Bt[n][k], At[m][k], acc[ai][bj][m][n], 0, 0, 0); __builtin_amdgcn_s_setprio(0); } while (0)
; #define PG8_WAIT_V(n) asm volatile("s_waitcnt vmcnt(" #n ")" ::: "memory")
; #define PG8_WAIT_L(n) asm volatile("s_waitcnt lgkmcnt(" #n ")" ::: "memory")
; #define PG8_BAR __builtin_amdgcn_s_barrier()
; #define PG8_SCHED __builtin_amdgcn_sched_barrier(0)
; template <class Epi, class Sched, bool ALIGN_EPI = false, bool SP2 = false>
; __device__ __forceinline__ void gemm_phase(PG8_LAS unsigned char* lds, const Gemm g, const Sched& S, const Epi& E) {
;     ...
;         for (int t = 0; t < nt; t += 2) {
;             const bool last = (t == nt - 2);
;             const char* a1 = cA + (size_t)(t + 1) * kstep;
;     ...
;             PG8_LDA(At, 1, 1); PG8_STAGE(PG8_SB(1, 0), b3, voffB); PG8_STAGE(PG8_SB(1, 1), b3 + hstep, voffB); PG8_STAGE(PG8_SA(1, 0), a3, voffA);
;             PG8_WAIT_V(8); PG8_WAIT_L(0); PG8_BAR; PG8_MMA(1, 0, At, B0); PG8_MMA(1, 1, At, B1); PG8_BAR; PG8_SCHED;
	s_setprio 0
	s_add_i32 s10, s10, s63
	v_lshl_add_u64 v[190:191], v[190:191], 0, s[36:37]
	s_mov_b32 m0, s10
	ds_read_b128 v[182:185], v165 offset:49152
	ds_read_b128 v[186:189], v165 offset:50176
	ds_read_b128 v[194:197], v165 offset:51200
	ds_read_b128 v[198:201], v165 offset:52224
	ds_read_b128 v[202:205], v165 offset:53248
	ds_read_b128 v[206:209], v165 offset:54272
	ds_read_b128 v[210:213], v165 offset:55296
	ds_read_b128 v[214:217], v165 offset:56320
	global_load_lds_dwordx4 v[190:191], off
	s_add_i32 m0, s10, 0x2000
	s_add_u32 s58, s58, 0x40080
	v_lshl_add_u64 v[190:191], v[218:219], 0, s[36:37]
	s_addc_u32 s59, s59, 0
	s_add_i32 s10, s11, s63
	global_load_lds_dwordx4 v[190:191], off
	v_lshl_add_u64 v[190:191], s[58:59], 0, v[146:147]
	s_mov_b32 m0, s10
	s_nop 0
	global_load_lds_dwordx4 v[190:191], off
	v_lshl_add_u64 v[190:191], s[58:59], 0, v[150:151]
	s_add_i32 m0, s10, 0x2000
	s_nop 0
	global_load_lds_dwordx4 v[190:191], off
	v_lshl_add_u64 v[190:191], v[220:221], 0, s[36:37]
	s_mov_b32 m0, s70
	s_nop 0
	global_load_lds_dwordx4 v[190:191], off
	v_lshl_add_u64 v[190:191], v[222:223], 0, s[36:37]
	s_mov_b32 m0, s71
	s_nop 0
	global_load_lds_dwordx4 v[190:191], off
	s_waitcnt vmcnt(8)
	s_waitcnt lgkmcnt(0)
	s_setprio 1
	s_barrier
	v_mfma_f32_16x16x32_bf16 v[60:63], v[128:131], v[182:185], v[60:63]
	v_mfma_f32_16x16x32_bf16 v[56:59], v[136:139], v[182:185], v[56:59]
	v_mfma_f32_16x16x32_bf16 v[48:51], v[128:131], v[194:197], v[48:51]
	v_mfma_f32_16x16x32_bf16 v[40:43], v[136:139], v[194:197], v[40:43]
	v_mfma_f32_16x16x32_bf16 v[32:35], v[128:131], v[202:205], v[32:35]
	v_mfma_f32_16x16x32_bf16 v[24:27], v[136:139], v[202:205], v[24:27]
	v_mfma_f32_16x16x32_bf16 v[16:19], v[128:131], v[210:213], v[16:19]
	v_mfma_f32_16x16x32_bf16 v[8:11], v[136:139], v[210:213], v[8:11]
	v_mfma_f32_16x16x32_bf16 v[60:63], v[132:135], v[186:189], v[60:63]
	v_mfma_f32_16x16x32_bf16 v[56:59], v[140:143], v[186:189], v[56:59]
	v_mfma_f32_16x16x32_bf16 v[48:51], v[132:135], v[198:201], v[48:51]
	v_mfma_f32_16x16x32_bf16 v[40:43], v[140:143], v[198:201], v[40:43]
	v_mfma_f32_16x16x32_bf16 v[32:35], v[132:135], v[206:209], v[32:35]
	v_mfma_f32_16x16x32_bf16 v[24:27], v[140:143], v[206:209], v[24:27]
	v_mfma_f32_16x16x32_bf16 v[16:19], v[132:135], v[214:217], v[16:19]
	v_mfma_f32_16x16x32_bf16 v[8:11], v[140:143], v[214:217], v[8:11]
	s_setprio 0
	s_setprio 1
	v_mfma_f32_16x16x32_bf16 v[52:55], v[166:169], v[182:185], v[52:55]
	v_mfma_f32_16x16x32_bf16 v[44:47], v[174:177], v[182:185], v[44:47]
	v_mfma_f32_16x16x32_bf16 v[36:39], v[166:169], v[194:197], v[36:39]
	v_mfma_f32_16x16x32_bf16 v[28:31], v[174:177], v[194:197], v[28:31]
	v_mfma_f32_16x16x32_bf16 v[20:23], v[166:169], v[202:205], v[20:23]
	v_mfma_f32_16x16x32_bf16 v[12:15], v[174:177], v[202:205], v[12:15]
	v_mfma_f32_16x16x32_bf16 v[4:7], v[166:169], v[210:213], v[4:7]
	v_mfma_f32_16x16x32_bf16 v[0:3], v[174:177], v[210:213], v[0:3]
	v_mfma_f32_16x16x32_bf16 v[52:55], v[170:173], v[186:189], v[52:55]
	v_mfma_f32_16x16x32_bf16 v[44:47], v[178:181], v[186:189], v[44:47]
	v_mfma_f32_16x16x32_bf16 v[36:39], v[170:173], v[198:201], v[36:39]
	v_mfma_f32_16x16x32_bf16 v[28:31], v[178:181], v[198:201], v[28:31]
	v_mfma_f32_16x16x32_bf16 v[20:23], v[170:173], v[206:209], v[20:23]
	v_mfma_f32_16x16x32_bf16 v[12:15], v[178:181], v[206:209], v[12:15]
	v_mfma_f32_16x16x32_bf16 v[4:7], v[170:173], v[214:217], v[4:7]
	v_mfma_f32_16x16x32_bf16 v[0:3], v[178:181], v[214:217], v[0:3]
	s_barrier
	s_setprio 0
	s_add_i32 s76, s76, 2
	s_add_u32 s56, s56, 0x100
	s_addc_u32 s57, s57, 0
	s_add_u32 s49, s49, 0x100
	s_addc_u32 s51, s51, 0
	s_cmp_gt_u32 s76, 13
	s_cbranch_scc0 .LBB0_200
	s_and_b64 vcc, exec, s[44:45]
	s_cbranch_vccz .LBB0_203
	s_barrier

; #define PG8_STAGE(bufoff, gbase, voff) do { _Pragma("unroll") for (int _i = 0; _i < 2; ++_i) \
;         __builtin_amdgcn_global_load_lds((const unsigned*)((const char*)(gbase) + (voff)[_i]), (PG8_LAS unsigned*)(lds + (bufoff) + ldsw + _i * 8192), 16, 0, 0); } while (0)
; #define PG8_LDA(dst, b, h) do { _Pragma("unroll") for (int m = 0; m < 4; ++m) _Pragma("unroll") for (int k = 0; k < 2; ++k) dst[m][k] = *(const PG8_LAS bf16x8*)(lds + PG8_SA(b, h) + aoff + m * 2048 + k * 1024); } while (0)
; #define PG8_LDB(dst, b, h) do { _Pragma("unroll") for (int n = 0; n < 2; ++n) _Pragma("unroll") for (int k = 0; k < 2; ++k) dst[n][k] = *(const PG8_LAS bf16x8*)(lds + PG8_SB(b, h) + boff + n * 2048 + k * 1024); } while (0)
; #define PG8_MMA(ai, bj, At, Bt) do { __builtin_amdgcn_s_setprio(1); _Pragma("unroll") for (int m = 0; m < 4; ++m) _Pragma("unroll") for (int n = 0; n < 2; ++n) _Pragma("unroll") for (int k = 0; k < 2; ++k) \
;         acc[ai][bj][m][n] = __builtin_amdgcn_mfma_f32_16x16x32_bf16(Bt[n][k], At[m][k], acc[ai][bj][m][n], 0, 0, 0); __builtin_amdgcn_s_setprio(0); } while (0)
; #define PG8_WAIT_V(n) asm volatile("s_waitcnt vmcnt(" #n ")" ::: "memory")
; #define PG8_WAIT_L(n) asm volatile("s_waitcnt lgkmcnt(" #n ")" ::: "memory")
; template <class Epi, class Sched, bool ALIGN_EPI = false, bool SP2 = false>
; __device__ __forceinline__ void gemm_phase(PG8_LAS unsigned char* lds, const Gemm g, const Sched& S, const Epi& E) {
;     ...
;             const bool last = (t == nt - 2);
;             const char* a1 = cA + (size_t)(t + 1) * kstep;
;             const char* a2 = last ? nA : cA + (size_t)(t + 2) * kstep; const char* b2 = last ? nB : cB + (size_t)(t + 2) * kstep;
;             const char* a3 = a2 + kstep; const char* b3 = b2 + kstep;
;             if (last && has_next) S.a_ready(nxt);
;             if constexpr (SP2) {
;             PG8_LDB(B0, 0, 0); PG8_LDB(B1, 0, 1); PG8_SCHED; PG8_LDA(At, 0, 0); PG8_STAGE(PG8_SA(1, 1), a1 + hstep, voffA);
;             PG8_WAIT_V(8); PG8_WAIT_L(0); PG8_BAR; PG8_MMA(0, 0, At, B0); PG8_MMA(0, 1, At, B1); PG8_BAR; PG8_SCHED;
;             PG8_LDA(At, 0, 1); PG8_STAGE(PG8_SB(0, 0), b2, voffB); PG8_STAGE(PG8_SB(0, 1), b2 + hstep, voffB); PG8_STAGE(PG8_SA(0, 0), a2, voffA);
;             PG8_WAIT_V(8); PG8_WAIT_L(0); PG8_BAR; PG8_MMA(1, 0, At, B0); PG8_MMA(1, 1, At, B1); PG8_BAR; PG8_SCHED;
.LBB0_488:
	s_add_u32 s10, s34, 0xfffc0080
	s_addc_u32 s11, s35, -1
	s_add_i32 s77, 0, 0x10000
	s_cmp_eq_u32 s76, 4
	s_cselect_b32 s53, s45, s11
	s_cselect_b32 s52, s44, s10
	s_cselect_b32 s51, s49, s75
	s_cselect_b32 s50, s48, s19
	s_add_i32 s78, 0, 0x14000
	v_add_u32_e32 v140, s77, v246
	v_add_u32_e32 v156, s77, v246
	v_add_u32_e32 v156, 0x1000, v156
	ds_read_b128 v[128:131], v140
	ds_read_b128 v[132:135], v140 offset:1024
	ds_read_b128 v[136:139], v140 offset:2048
	ds_read_b128 v[140:143], v140 offset:3072
	ds_read_b128 v[144:147], v156
	ds_read_b128 v[148:151], v156 offset:1024
	ds_read_b128 v[152:155], v156 offset:2048
	ds_read_b128 v[156:159], v156 offset:3072
	v_lshl_add_u64 v[208:209], s[34:35], 0, v[204:205]
	s_add_i32 m0, s55, 0xc000
	ds_read_b128 v[160:163], v249
	ds_read_b128 v[164:167], v249 offset:1024
	ds_read_b128 v[168:171], v249 offset:2048
	ds_read_b128 v[172:175], v249 offset:3072
	ds_read_b128 v[176:179], v249 offset:4096
	ds_read_b128 v[180:183], v249 offset:5120
	ds_read_b128 v[184:187], v249 offset:6144
	ds_read_b128 v[188:191], v249 offset:7168
	global_load_lds_dwordx4 v[208:209], off
	v_lshl_add_u64 v[208:209], s[34:35], 0, v[206:207]
	s_add_i32 m0, s55, 0xe000
	s_nop 0
	global_load_lds_dwordx4 v[208:209], off
	s_waitcnt vmcnt(8)
	s_waitcnt lgkmcnt(0)
	s_setprio 1
	s_barrier
	v_mfma_f32_16x16x32_bf16 v[124:127], v[128:131], v[160:163], v[124:127]
	v_mfma_f32_16x16x32_bf16 v[120:123], v[136:139], v[160:163], v[120:123]
	v_mfma_f32_16x16x32_bf16 v[116:119], v[128:131], v[168:171], v[116:119]
	v_mfma_f32_16x16x32_bf16 v[112:115], v[136:139], v[168:171], v[112:115]
	v_mfma_f32_16x16x32_bf16 v[108:111], v[128:131], v[176:179], v[108:111]
	v_mfma_f32_16x16x32_bf16 v[104:107], v[136:139], v[176:179], v[104:107]
	v_mfma_f32_16x16x32_bf16 v[100:103], v[128:131], v[184:187], v[100:103]
	v_mfma_f32_16x16x32_bf16 v[96:99], v[136:139], v[184:187], v[96:99]
	v_mfma_f32_16x16x32_bf16 v[124:127], v[132:135], v[164:167], v[124:127]
	v_mfma_f32_16x16x32_bf16 v[120:123], v[140:143], v[164:167], v[120:123]
	v_mfma_f32_16x16x32_bf16 v[116:119], v[132:135], v[172:175], v[116:119]
	v_mfma_f32_16x16x32_bf16 v[112:115], v[140:143], v[172:175], v[112:115]
	v_mfma_f32_16x16x32_bf16 v[108:111], v[132:135], v[180:183], v[108:111]
	v_mfma_f32_16x16x32_bf16 v[104:107], v[140:143], v[180:183], v[104:107]
	v_mfma_f32_16x16x32_bf16 v[100:103], v[132:135], v[188:191], v[100:103]
	v_mfma_f32_16x16x32_bf16 v[96:99], v[140:143], v[188:191], v[96:99]
	s_setprio 0
	s_setprio 1
	v_mfma_f32_16x16x32_bf16 v[92:95], v[144:147], v[160:163], v[92:95]
	v_mfma_f32_16x16x32_bf16 v[88:91], v[152:155], v[160:163], v[88:91]
	v_mfma_f32_16x16x32_bf16 v[84:87], v[144:147], v[168:171], v[84:87]
	v_mfma_f32_16x16x32_bf16 v[80:83], v[152:155], v[168:171], v[80:83]
	v_mfma_f32_16x16x32_bf16 v[76:79], v[144:147], v[176:179], v[76:79]
	v_mfma_f32_16x16x32_bf16 v[72:75], v[152:155], v[176:179], v[72:75]
	v_mfma_f32_16x16x32_bf16 v[68:71], v[144:147], v[184:187], v[68:71]
	v_mfma_f32_16x16x32_bf16 v[64:67], v[152:155], v[184:187], v[64:67]
	v_mfma_f32_16x16x32_bf16 v[92:95], v[148:151], v[164:167], v[92:95]
	v_mfma_f32_16x16x32_bf16 v[88:91], v[156:159], v[164:167], v[88:91]
	v_mfma_f32_16x16x32_bf16 v[84:87], v[148:151], v[172:175], v[84:87]
	v_mfma_f32_16x16x32_bf16 v[80:83], v[156:159], v[172:175], v[80:83]
	v_mfma_f32_16x16x32_bf16 v[76:79], v[148:151], v[180:183], v[76:79]
	v_mfma_f32_16x16x32_bf16 v[72:75], v[156:159], v[180:183], v[72:75]
	v_mfma_f32_16x16x32_bf16 v[68:71], v[148:151], v[188:191], v[68:71]
	v_mfma_f32_16x16x32_bf16 v[64:67], v[156:159], v[188:191], v[64:67]
	s_barrier
	s_setprio 0
	s_add_i32 s10, s77, s14
	v_lshl_add_u64 v[208:209], s[50:51], 0, v[198:199]
	s_mov_b32 m0, s10
	ds_read_b128 v[160:163], v249 offset:16384
	ds_read_b128 v[164:167], v249 offset:17408
	ds_read_b128 v[168:171], v249 offset:18432
	ds_read_b128 v[172:175], v249 offset:19456
	ds_read_b128 v[176:179], v249 offset:20480
	ds_read_b128 v[180:183], v249 offset:21504
	ds_read_b128 v[184:187], v249 offset:22528
	ds_read_b128 v[188:191], v249 offset:23552
	global_load_lds_dwordx4 v[208:209], off
	s_add_i32 m0, s10, 0x2000
	s_add_u32 s10, s50, 0x40000
	v_lshl_add_u64 v[210:211], s[50:51], 0, v[194:195]
	s_addc_u32 s11, s51, 0
	s_add_i32 s77, s78, s14
	global_load_lds_dwordx4 v[210:211], off
	v_lshl_add_u64 v[212:213], s[10:11], 0, v[198:199]
	s_mov_b32 m0, s77
	v_lshl_add_u64 v[214:215], s[52:53], 0, v[196:197]
	global_load_lds_dwordx4 v[212:213], off
	v_lshl_add_u64 v[212:213], s[10:11], 0, v[194:195]
	s_add_i32 m0, s77, 0x2000
	s_nop 0
	global_load_lds_dwordx4 v[212:213], off
	v_lshl_add_u64 v[212:213], s[52:53], 0, v[200:201]
	s_mov_b32 m0, s55
	s_nop 0
	global_load_lds_dwordx4 v[212:213], off
	s_mov_b32 m0, s58
	s_nop 0
	global_load_lds_dwordx4 v[214:215], off
	s_waitcnt vmcnt(8)
	s_waitcnt lgkmcnt(0)
	s_setprio 1
	s_barrier
; #define PG8_STAGE(bufoff, gbase, voff) do { _Pragma("unroll") for (int _i = 0; _i < 2; ++_i) \
;         __builtin_amdgcn_global_load_lds((const unsigned*)((const char*)(gbase) + (voff)[_i]), (PG8_LAS unsigned*)(lds + (bufoff) + ldsw + _i * 8192), 16, 0, 0); } while (0)
; #define PG8_LDA(dst, b, h) do { _Pragma("unroll") for (int m = 0; m < 4; ++m) _Pragma("unroll") for (int k = 0; k < 2; ++k) dst[m][k] = *(const PG8_LAS bf16x8*)(lds + PG8_SA(b, h) + aoff + m * 2048 + k * 1024); } while (0)
; #define PG8_LDB(dst, b, h) do { _Pragma("unroll") for (int n = 0; n < 2; ++n) _Pragma("unroll") for (int k = 0; k < 2; ++k) dst[n][k] = *(const PG8_LAS bf16x8*)(lds + PG8_SB(b, h) + boff + n * 2048 + k * 1024); } while (0)
; #define PG8_MMA(ai, bj, At, Bt) do { __builtin_amdgcn_s_setprio(1); _Pragma("unroll") for (int m = 0; m < 4; ++m) _Pragma("unroll") for (int n = 0; n < 2; ++n) _Pragma("unroll") for (int k = 0; k < 2; ++k) \
;         acc[ai][bj][m][n] = __builtin_amdgcn_mfma_f32_16x16x32_bf16(Bt[n][k], At[m][k], acc[ai][bj][m][n], 0, 0, 0); __builtin_amdgcn_s_setprio(0); } while (0)
; #define PG8_WAIT_V(n) asm volatile("s_waitcnt vmcnt(" #n ")" ::: "memory")
; #define PG8_WAIT_L(n) asm volatile("s_waitcnt lgkmcnt(" #n ")" ::: "memory")
; #define PG8_BAR __builtin_amdgcn_s_barrier()
; #define PG8_SCHED __builtin_amdgcn_sched_barrier(0)
; template <class Epi, class Sched, bool ALIGN_EPI = false, bool SP2 = false>
; __device__ __forceinline__ void gemm_phase(PG8_LAS unsigned char* lds, const Gemm g, const Sched& S, const Epi& E) {
;     ...
;             PG8_WAIT_V(8); PG8_WAIT_L(0); PG8_BAR; PG8_MMA(1, 0, At, B0); PG8_MMA(1, 1, At, B1); PG8_BAR; PG8_SCHED;
;             PG8_LDB(B0, 1, 0); PG8_LDB(B1, 1, 1); PG8_SCHED; PG8_LDA(At, 1, 0); PG8_STAGE(PG8_SA(0, 1), a2 + hstep, voffA);
;             PG8_WAIT_V(8); PG8_WAIT_L(0); PG8_BAR; PG8_MMA(0, 0, At, B0); PG8_MMA(0, 1, At, B1); PG8_BAR; PG8_SCHED;
	v_mfma_f32_16x16x32_bf16 v[60:63], v[128:131], v[160:163], v[60:63]
	v_mfma_f32_16x16x32_bf16 v[56:59], v[136:139], v[160:163], v[56:59]
	v_mfma_f32_16x16x32_bf16 v[52:55], v[128:131], v[168:171], v[52:55]
	v_mfma_f32_16x16x32_bf16 v[48:51], v[136:139], v[168:171], v[48:51]
	v_mfma_f32_16x16x32_bf16 v[44:47], v[128:131], v[176:179], v[44:47]
	v_mfma_f32_16x16x32_bf16 v[40:43], v[136:139], v[176:179], v[40:43]
	v_mfma_f32_16x16x32_bf16 v[36:39], v[128:131], v[184:187], v[36:39]
	v_mfma_f32_16x16x32_bf16 v[32:35], v[136:139], v[184:187], v[32:35]
	v_mfma_f32_16x16x32_bf16 v[60:63], v[132:135], v[164:167], v[60:63]
	v_mfma_f32_16x16x32_bf16 v[56:59], v[140:143], v[164:167], v[56:59]
	v_mfma_f32_16x16x32_bf16 v[52:55], v[132:135], v[172:175], v[52:55]
	v_mfma_f32_16x16x32_bf16 v[48:51], v[140:143], v[172:175], v[48:51]
	v_mfma_f32_16x16x32_bf16 v[44:47], v[132:135], v[180:183], v[44:47]
	v_mfma_f32_16x16x32_bf16 v[40:43], v[140:143], v[180:183], v[40:43]
	v_mfma_f32_16x16x32_bf16 v[36:39], v[132:135], v[188:191], v[36:39]
	v_mfma_f32_16x16x32_bf16 v[32:35], v[140:143], v[188:191], v[32:35]
	s_setprio 0
	s_setprio 1
	v_mfma_f32_16x16x32_bf16 v[28:31], v[144:147], v[160:163], v[28:31]
	v_mfma_f32_16x16x32_bf16 v[24:27], v[152:155], v[160:163], v[24:27]
	v_mfma_f32_16x16x32_bf16 v[20:23], v[144:147], v[168:171], v[20:23]
	v_mfma_f32_16x16x32_bf16 v[16:19], v[152:155], v[168:171], v[16:19]
	v_mfma_f32_16x16x32_bf16 v[12:15], v[144:147], v[176:179], v[12:15]
	v_mfma_f32_16x16x32_bf16 v[8:11], v[152:155], v[176:179], v[8:11]
	v_mfma_f32_16x16x32_bf16 v[4:7], v[144:147], v[184:187], v[4:7]
	v_mfma_f32_16x16x32_bf16 v[0:3], v[152:155], v[184:187], v[0:3]
	v_mfma_f32_16x16x32_bf16 v[28:31], v[148:151], v[164:167], v[28:31]
	v_mfma_f32_16x16x32_bf16 v[24:27], v[156:159], v[164:167], v[24:27]
	v_mfma_f32_16x16x32_bf16 v[20:23], v[148:151], v[172:175], v[20:23]
	v_mfma_f32_16x16x32_bf16 v[16:19], v[156:159], v[172:175], v[16:19]
	v_mfma_f32_16x16x32_bf16 v[12:15], v[148:151], v[180:183], v[12:15]
	v_mfma_f32_16x16x32_bf16 v[8:11], v[156:159], v[180:183], v[8:11]
	v_mfma_f32_16x16x32_bf16 v[4:7], v[148:151], v[188:191], v[4:7]
	v_mfma_f32_16x16x32_bf16 v[0:3], v[156:159], v[188:191], v[0:3]
	s_barrier
	s_setprio 0
	s_add_i32 s77, 0, 0x18000
	s_add_i32 s78, 0, 0x1c000
	v_add_u32_e32 v140, s77, v246
	v_add_u32_e32 v156, s77, v246
	v_add_u32_e32 v156, 0x1000, v156
	ds_read_b128 v[128:131], v140
	ds_read_b128 v[132:135], v140 offset:1024
	ds_read_b128 v[136:139], v140 offset:2048
	ds_read_b128 v[140:143], v140 offset:3072
	ds_read_b128 v[144:147], v156
	ds_read_b128 v[148:151], v156 offset:1024
	ds_read_b128 v[152:155], v156 offset:2048
	ds_read_b128 v[156:159], v156 offset:3072
	s_add_u32 s10, s52, 0x40000
	s_addc_u32 s11, s53, 0
	s_mov_b32 m0, s59
	v_lshl_add_u64 v[216:217], s[10:11], 0, v[200:201]
	ds_read_b128 v[160:163], v249 offset:32768
	ds_read_b128 v[164:167], v249 offset:33792
	ds_read_b128 v[168:171], v249 offset:34816
	ds_read_b128 v[172:175], v249 offset:35840
	ds_read_b128 v[176:179], v249 offset:36864
	ds_read_b128 v[180:183], v249 offset:37888
	ds_read_b128 v[184:187], v249 offset:38912
	ds_read_b128 v[188:191], v249 offset:39936
	global_load_lds_dwordx4 v[216:217], off
	v_lshl_add_u64 v[216:217], s[10:11], 0, v[196:197]
	s_mov_b32 m0, s60
	s_nop 0
	global_load_lds_dwordx4 v[216:217], off
	s_waitcnt vmcnt(8)
	s_waitcnt lgkmcnt(0)
	s_setprio 1
	s_barrier
	v_mfma_f32_16x16x32_bf16 v[124:127], v[128:131], v[160:163], v[124:127]
	v_mfma_f32_16x16x32_bf16 v[120:123], v[136:139], v[160:163], v[120:123]
	v_mfma_f32_16x16x32_bf16 v[116:119], v[128:131], v[168:171], v[116:119]
	v_mfma_f32_16x16x32_bf16 v[112:115], v[136:139], v[168:171], v[112:115]
	v_mfma_f32_16x16x32_bf16 v[108:111], v[128:131], v[176:179], v[108:111]
	v_mfma_f32_16x16x32_bf16 v[104:107], v[136:139], v[176:179], v[104:107]
	v_mfma_f32_16x16x32_bf16 v[100:103], v[128:131], v[184:187], v[100:103]
	v_mfma_f32_16x16x32_bf16 v[96:99], v[136:139], v[184:187], v[96:99]
	v_mfma_f32_16x16x32_bf16 v[124:127], v[132:135], v[164:167], v[124:127]
	v_mfma_f32_16x16x32_bf16 v[120:123], v[140:143], v[164:167], v[120:123]
	v_mfma_f32_16x16x32_bf16 v[116:119], v[132:135], v[172:175], v[116:119]
	v_mfma_f32_16x16x32_bf16 v[112:115], v[140:143], v[172:175], v[112:115]
	v_mfma_f32_16x16x32_bf16 v[108:111], v[132:135], v[180:183], v[108:111]
	v_mfma_f32_16x16x32_bf16 v[104:107], v[140:143], v[180:183], v[104:107]
	v_mfma_f32_16x16x32_bf16 v[100:103], v[132:135], v[188:191], v[100:103]
	v_mfma_f32_16x16x32_bf16 v[96:99], v[140:143], v[188:191], v[96:99]
	s_setprio 0
	s_setprio 1
	v_mfma_f32_16x16x32_bf16 v[92:95], v[144:147], v[160:163], v[92:95]
	v_mfma_f32_16x16x32_bf16 v[88:91], v[152:155], v[160:163], v[88:91]
	v_mfma_f32_16x16x32_bf16 v[84:87], v[144:147], v[168:171], v[84:87]
	v_mfma_f32_16x16x32_bf16 v[80:83], v[152:155], v[168:171], v[80:83]
	v_mfma_f32_16x16x32_bf16 v[76:79], v[144:147], v[176:179], v[76:79]
	v_mfma_f32_16x16x32_bf16 v[72:75], v[152:155], v[176:179], v[72:75]
	v_mfma_f32_16x16x32_bf16 v[68:71], v[144:147], v[184:187], v[68:71]
	v_mfma_f32_16x16x32_bf16 v[64:67], v[152:155], v[184:187], v[64:67]
	v_mfma_f32_16x16x32_bf16 v[92:95], v[148:151], v[164:167], v[92:95]
	v_mfma_f32_16x16x32_bf16 v[88:91], v[156:159], v[164:167], v[88:91]
	v_mfma_f32_16x16x32_bf16 v[84:87], v[148:151], v[172:175], v[84:87]
	v_mfma_f32_16x16x32_bf16 v[80:83], v[156:159], v[172:175], v[80:83]
	v_mfma_f32_16x16x32_bf16 v[76:79], v[148:151], v[180:183], v[76:79]
	v_mfma_f32_16x16x32_bf16 v[72:75], v[156:159], v[180:183], v[72:75]
	v_mfma_f32_16x16x32_bf16 v[68:71], v[148:151], v[188:191], v[68:71]
	v_mfma_f32_16x16x32_bf16 v[64:67], v[156:159], v[188:191], v[64:67]
	s_barrier
; #define PG8_STAGE(bufoff, gbase, voff) do { _Pragma("unroll") for (int _i = 0; _i < 2; ++_i) \
;         __builtin_amdgcn_global_load_lds((const unsigned*)((const char*)(gbase) + (voff)[_i]), (PG8_LAS unsigned*)(lds + (bufoff) + ldsw + _i * 8192), 16, 0, 0); } while (0)
; #define PG8_LDA(dst, b, h) do { _Pragma("unroll") for (int m = 0; m < 4; ++m) _Pragma("unroll") for (int k = 0; k < 2; ++k) dst[m][k] = *(const PG8_LAS bf16x8*)(lds + PG8_SA(b, h) + aoff + m * 2048 + k * 1024); } while (0)
; #define PG8_MMA(ai, bj, At, Bt) do { __builtin_amdgcn_s_setprio(1); _Pragma("unroll") for (int m = 0; m < 4; ++m) _Pragma("unroll") for (int n = 0; n < 2; ++n) _Pragma("unroll") for (int k = 0; k < 2; ++k) \
;         acc[ai][bj][m][n] = __builtin_amdgcn_mfma_f32_16x16x32_bf16(Bt[n][k], At[m][k], acc[ai][bj][m][n], 0, 0, 0); __builtin_amdgcn_s_setprio(0); } while (0)
; #define PG8_WAIT_V(n) asm volatile("s_waitcnt vmcnt(" #n ")" ::: "memory")
; #define PG8_WAIT_L(n) asm volatile("s_waitcnt lgkmcnt(" #n ")" ::: "memory")
; #define PG8_BAR __builtin_amdgcn_s_barrier()
; #define PG8_SCHED __builtin_amdgcn_sched_barrier(0)
; template <class Epi, class Sched, bool ALIGN_EPI = false, bool SP2 = false>
; __device__ __forceinline__ void gemm_phase(PG8_LAS unsigned char* lds, const Gemm g, const Sched& S, const Epi& E) {
;     ...
;         for (int t = 0; t < nt; t += 2) {
;             const bool last = (t == nt - 2);
;             const char* a1 = cA + (size_t)(t + 1) * kstep;
;     ...
;             PG8_LDA(At, 1, 1); PG8_STAGE(PG8_SB(1, 0), b3, voffB); PG8_STAGE(PG8_SB(1, 1), b3 + hstep, voffB); PG8_STAGE(PG8_SA(1, 0), a3, voffA);
;             PG8_WAIT_V(8); PG8_WAIT_L(0); PG8_BAR; PG8_MMA(1, 0, At, B0); PG8_MMA(1, 1, At, B1); PG8_BAR; PG8_SCHED;
	s_setprio 0
	s_add_i32 s10, s77, s14
	v_lshl_add_u64 v[208:209], v[208:209], 0, s[36:37]
	s_mov_b32 m0, s10
	ds_read_b128 v[160:163], v249 offset:49152
	ds_read_b128 v[164:167], v249 offset:50176
	ds_read_b128 v[168:171], v249 offset:51200
	ds_read_b128 v[172:175], v249 offset:52224
	ds_read_b128 v[176:179], v249 offset:53248
	ds_read_b128 v[180:183], v249 offset:54272
	ds_read_b128 v[184:187], v249 offset:55296
	ds_read_b128 v[188:191], v249 offset:56320
	global_load_lds_dwordx4 v[208:209], off
	s_add_i32 m0, s10, 0x2000
	s_add_u32 s10, s50, 0x40080
	v_lshl_add_u64 v[208:209], v[210:211], 0, s[36:37]
	s_addc_u32 s11, s51, 0
	s_add_i32 s50, s78, s14
	global_load_lds_dwordx4 v[208:209], off
	v_lshl_add_u64 v[208:209], s[10:11], 0, v[198:199]
	s_mov_b32 m0, s50
	s_nop 0
	global_load_lds_dwordx4 v[208:209], off
	v_lshl_add_u64 v[208:209], s[10:11], 0, v[194:195]
	s_add_i32 m0, s50, 0x2000
	s_nop 0
	global_load_lds_dwordx4 v[208:209], off
	v_lshl_add_u64 v[208:209], v[212:213], 0, s[36:37]
	s_mov_b32 m0, s65
	s_nop 0
	global_load_lds_dwordx4 v[208:209], off
	v_lshl_add_u64 v[208:209], v[214:215], 0, s[36:37]
	s_mov_b32 m0, s66
	s_nop 0
	global_load_lds_dwordx4 v[208:209], off
	s_waitcnt vmcnt(8)
	s_waitcnt lgkmcnt(0)
	s_setprio 1
	s_barrier
	v_mfma_f32_16x16x32_bf16 v[60:63], v[128:131], v[160:163], v[60:63]
	v_mfma_f32_16x16x32_bf16 v[56:59], v[136:139], v[160:163], v[56:59]
	v_mfma_f32_16x16x32_bf16 v[52:55], v[128:131], v[168:171], v[52:55]
	v_mfma_f32_16x16x32_bf16 v[48:51], v[136:139], v[168:171], v[48:51]
	v_mfma_f32_16x16x32_bf16 v[44:47], v[128:131], v[176:179], v[44:47]
	v_mfma_f32_16x16x32_bf16 v[40:43], v[136:139], v[176:179], v[40:43]
	v_mfma_f32_16x16x32_bf16 v[36:39], v[128:131], v[184:187], v[36:39]
	v_mfma_f32_16x16x32_bf16 v[32:35], v[136:139], v[184:187], v[32:35]
	v_mfma_f32_16x16x32_bf16 v[60:63], v[132:135], v[164:167], v[60:63]
	v_mfma_f32_16x16x32_bf16 v[56:59], v[140:143], v[164:167], v[56:59]
	v_mfma_f32_16x16x32_bf16 v[52:55], v[132:135], v[172:175], v[52:55]
	v_mfma_f32_16x16x32_bf16 v[48:51], v[140:143], v[172:175], v[48:51]
	v_mfma_f32_16x16x32_bf16 v[44:47], v[132:135], v[180:183], v[44:47]
	v_mfma_f32_16x16x32_bf16 v[40:43], v[140:143], v[180:183], v[40:43]
	v_mfma_f32_16x16x32_bf16 v[36:39], v[132:135], v[188:191], v[36:39]
	v_mfma_f32_16x16x32_bf16 v[32:35], v[140:143], v[188:191], v[32:35]
	s_setprio 0
	s_setprio 1
	v_mfma_f32_16x16x32_bf16 v[28:31], v[144:147], v[160:163], v[28:31]
	v_mfma_f32_16x16x32_bf16 v[24:27], v[152:155], v[160:163], v[24:27]
	v_mfma_f32_16x16x32_bf16 v[20:23], v[144:147], v[168:171], v[20:23]
	v_mfma_f32_16x16x32_bf16 v[16:19], v[152:155], v[168:171], v[16:19]
	v_mfma_f32_16x16x32_bf16 v[12:15], v[144:147], v[176:179], v[12:15]
	v_mfma_f32_16x16x32_bf16 v[8:11], v[152:155], v[176:179], v[8:11]
	v_mfma_f32_16x16x32_bf16 v[4:7], v[144:147], v[184:187], v[4:7]
	v_mfma_f32_16x16x32_bf16 v[0:3], v[152:155], v[184:187], v[0:3]
	v_mfma_f32_16x16x32_bf16 v[28:31], v[148:151], v[164:167], v[28:31]
	v_mfma_f32_16x16x32_bf16 v[24:27], v[156:159], v[164:167], v[24:27]
	v_mfma_f32_16x16x32_bf16 v[20:23], v[148:151], v[172:175], v[20:23]
	v_mfma_f32_16x16x32_bf16 v[16:19], v[156:159], v[172:175], v[16:19]
	v_mfma_f32_16x16x32_bf16 v[12:15], v[148:151], v[180:183], v[12:15]
	v_mfma_f32_16x16x32_bf16 v[8:11], v[156:159], v[180:183], v[8:11]
	v_mfma_f32_16x16x32_bf16 v[4:7], v[148:151], v[188:191], v[4:7]
	v_mfma_f32_16x16x32_bf16 v[0:3], v[156:159], v[188:191], v[0:3]
	s_barrier
	s_setprio 0
	s_add_i32 s76, s76, 2
	s_add_u32 s34, s34, 0x100
	s_addc_u32 s35, s35, 0
	s_add_u32 s19, s19, 0x100
	s_addc_u32 s75, s75, 0
	s_cmp_gt_u32 s76, 5
	s_cbranch_scc0 .LBB0_488
	s_and_b64 vcc, exec, s[24:25]
	s_cbranch_vccz .LBB0_491
	s_barrier

; #define PG8_STAGE(bufoff, gbase, voff) do { _Pragma("unroll") for (int _i = 0; _i < 2; ++_i) \
;         __builtin_amdgcn_global_load_lds((const unsigned*)((const char*)(gbase) + (voff)[_i]), (PG8_LAS unsigned*)(lds + (bufoff) + ldsw + _i * 8192), 16, 0, 0); } while (0)
; #define PG8_LDA(dst, b, h) do { _Pragma("unroll") for (int m = 0; m < 4; ++m) _Pragma("unroll") for (int k = 0; k < 2; ++k) dst[m][k] = *(const PG8_LAS bf16x8*)(lds + PG8_SA(b, h) + aoff + m * 2048 + k * 1024); } while (0)
; #define PG8_LDB(dst, b, h) do { _Pragma("unroll") for (int n = 0; n < 2; ++n) _Pragma("unroll") for (int k = 0; k < 2; ++k) dst[n][k] = *(const PG8_LAS bf16x8*)(lds + PG8_SB(b, h) + boff + n * 2048 + k * 1024); } while (0)
; #define PG8_MMA(ai, bj, At, Bt) do { __builtin_amdgcn_s_setprio(1); _Pragma("unroll") for (int m = 0; m < 4; ++m) _Pragma("unroll") for (int n = 0; n < 2; ++n) _Pragma("unroll") for (int k = 0; k < 2; ++k) \
;         acc[ai][bj][m][n] = __builtin_amdgcn_mfma_f32_16x16x32_bf16(Bt[n][k], At[m][k], acc[ai][bj][m][n], 0, 0, 0); __builtin_amdgcn_s_setprio(0); } while (0)
; #define PG8_WAIT_V(n) asm volatile("s_waitcnt vmcnt(" #n ")" ::: "memory")
; #define PG8_WAIT_L(n) asm volatile("s_waitcnt lgkmcnt(" #n ")" ::: "memory")
; template <class Epi, class Sched, bool ALIGN_EPI = false, bool SP2 = false>
; __device__ __forceinline__ void gemm_phase(PG8_LAS unsigned char* lds, const Gemm g, const Sched& S, const Epi& E) {
;     ...
;             const bool last = (t == nt - 2);
;             const char* a1 = cA + (size_t)(t + 1) * kstep;
;             const char* a2 = last ? nA : cA + (size_t)(t + 2) * kstep; const char* b2 = last ? nB : cB + (size_t)(t + 2) * kstep;
;             const char* a3 = a2 + kstep; const char* b3 = b2 + kstep;
;             if (last && has_next) S.a_ready(nxt);
;             if constexpr (SP2) {
;             PG8_LDB(B0, 0, 0); PG8_LDB(B1, 0, 1); PG8_SCHED; PG8_LDA(At, 0, 0); PG8_STAGE(PG8_SA(1, 1), a1 + hstep, voffA);
;             PG8_WAIT_V(8); PG8_WAIT_L(0); PG8_BAR; PG8_MMA(0, 0, At, B0); PG8_MMA(0, 1, At, B1); PG8_BAR; PG8_SCHED;
;             PG8_LDA(At, 0, 1); PG8_STAGE(PG8_SB(0, 0), b2, voffB); PG8_STAGE(PG8_SB(0, 1), b2 + hstep, voffB); PG8_STAGE(PG8_SA(0, 0), a2, voffA);
;             PG8_WAIT_V(8); PG8_WAIT_L(0); PG8_BAR; PG8_MMA(1, 0, At, B0); PG8_MMA(1, 1, At, B1); PG8_BAR; PG8_SCHED;
.LBB0_577:
	s_add_u32 s10, s44, 0xfffc0080
	s_addc_u32 s11, s45, -1
	s_add_i32 s64, 0, 0x10000
	s_cmp_eq_u32 s63, 12
	s_cselect_b32 s49, s29, s11
	s_cselect_b32 s48, s43, s10
	v_add_u32_e32 v146, s64, v149
	s_cselect_b32 s47, s27, s62
	s_cselect_b32 s46, s60, s61
	s_add_i32 s65, 0, 0x14000
	ds_read_b128 v[128:131], v146
	ds_read_b128 v[154:157], v146 offset:1024
	ds_read_b128 v[158:161], v146 offset:2048
	ds_read_b128 v[162:165], v146 offset:3072
	v_add_u32_e32 v146, s65, v149
	ds_read_b128 v[166:169], v146
	ds_read_b128 v[170:173], v146 offset:1024
	ds_read_b128 v[174:177], v146 offset:2048
	ds_read_b128 v[178:181], v146 offset:3072
	v_lshl_add_u64 v[190:191], s[44:45], 0, v[142:143]
	s_add_i32 m0, s51, 0xc000
	ds_read_b128 v[182:185], v153
	ds_read_b128 v[186:189], v153 offset:1024
	ds_read_b128 v[194:197], v153 offset:2048
	ds_read_b128 v[198:201], v153 offset:3072
	ds_read_b128 v[202:205], v153 offset:4096
	ds_read_b128 v[206:209], v153 offset:5120
	ds_read_b128 v[210:213], v153 offset:6144
	ds_read_b128 v[214:217], v153 offset:7168
	global_load_lds_dwordx4 v[190:191], off
	v_lshl_add_u64 v[190:191], s[44:45], 0, v[144:145]
	s_add_i32 m0, s51, 0xe000
	s_nop 0
	global_load_lds_dwordx4 v[190:191], off
	s_waitcnt vmcnt(8)
	s_waitcnt lgkmcnt(0)
	s_setprio 1
	s_barrier
	v_mfma_f32_16x16x32_bf16 v[124:127], v[128:131], v[182:185], v[124:127]
	v_mfma_f32_16x16x32_bf16 v[116:119], v[158:161], v[182:185], v[116:119]
	v_mfma_f32_16x16x32_bf16 v[108:111], v[128:131], v[194:197], v[108:111]
	v_mfma_f32_16x16x32_bf16 v[100:103], v[158:161], v[194:197], v[100:103]
	v_mfma_f32_16x16x32_bf16 v[92:95], v[128:131], v[202:205], v[92:95]
	v_mfma_f32_16x16x32_bf16 v[84:87], v[158:161], v[202:205], v[84:87]
	v_mfma_f32_16x16x32_bf16 v[76:79], v[128:131], v[210:213], v[76:79]
	v_mfma_f32_16x16x32_bf16 v[68:71], v[158:161], v[210:213], v[68:71]
	v_mfma_f32_16x16x32_bf16 v[124:127], v[154:157], v[186:189], v[124:127]
	v_mfma_f32_16x16x32_bf16 v[116:119], v[162:165], v[186:189], v[116:119]
	v_mfma_f32_16x16x32_bf16 v[108:111], v[154:157], v[198:201], v[108:111]
	v_mfma_f32_16x16x32_bf16 v[100:103], v[162:165], v[198:201], v[100:103]
	v_mfma_f32_16x16x32_bf16 v[92:95], v[154:157], v[206:209], v[92:95]
	v_mfma_f32_16x16x32_bf16 v[84:87], v[162:165], v[206:209], v[84:87]
	v_mfma_f32_16x16x32_bf16 v[76:79], v[154:157], v[214:217], v[76:79]
	v_mfma_f32_16x16x32_bf16 v[68:71], v[162:165], v[214:217], v[68:71]
	s_setprio 0
	s_setprio 1
	v_mfma_f32_16x16x32_bf16 v[120:123], v[166:169], v[182:185], v[120:123]
	v_mfma_f32_16x16x32_bf16 v[112:115], v[174:177], v[182:185], v[112:115]
	v_mfma_f32_16x16x32_bf16 v[104:107], v[166:169], v[194:197], v[104:107]
	v_mfma_f32_16x16x32_bf16 v[96:99], v[174:177], v[194:197], v[96:99]
	v_mfma_f32_16x16x32_bf16 v[88:91], v[166:169], v[202:205], v[88:91]
	v_mfma_f32_16x16x32_bf16 v[80:83], v[174:177], v[202:205], v[80:83]
	v_mfma_f32_16x16x32_bf16 v[72:75], v[166:169], v[210:213], v[72:75]
	v_mfma_f32_16x16x32_bf16 v[64:67], v[174:177], v[210:213], v[64:67]
	v_mfma_f32_16x16x32_bf16 v[120:123], v[170:173], v[186:189], v[120:123]
	v_mfma_f32_16x16x32_bf16 v[112:115], v[178:181], v[186:189], v[112:115]
	v_mfma_f32_16x16x32_bf16 v[104:107], v[170:173], v[198:201], v[104:107]
	v_mfma_f32_16x16x32_bf16 v[96:99], v[178:181], v[198:201], v[96:99]
	v_mfma_f32_16x16x32_bf16 v[88:91], v[170:173], v[206:209], v[88:91]
	v_mfma_f32_16x16x32_bf16 v[80:83], v[178:181], v[206:209], v[80:83]
	v_mfma_f32_16x16x32_bf16 v[72:75], v[170:173], v[214:217], v[72:75]
	v_mfma_f32_16x16x32_bf16 v[64:67], v[178:181], v[214:217], v[64:67]
	s_barrier
	s_setprio 0
	s_add_i32 s10, s64, s19
	v_lshl_add_u64 v[190:191], s[46:47], 0, v[136:137]
	s_mov_b32 m0, s10
	ds_read_b128 v[182:185], v153 offset:16384
	ds_read_b128 v[186:189], v153 offset:17408
	ds_read_b128 v[194:197], v153 offset:18432
	ds_read_b128 v[198:201], v153 offset:19456
	ds_read_b128 v[202:205], v153 offset:20480
	ds_read_b128 v[206:209], v153 offset:21504
	ds_read_b128 v[210:213], v153 offset:22528
	ds_read_b128 v[214:217], v153 offset:23552
	global_load_lds_dwordx4 v[190:191], off
	s_add_i32 m0, s10, 0x2000
	s_add_u32 s10, s46, 0x40000
	v_lshl_add_u64 v[218:219], s[46:47], 0, v[132:133]
	s_addc_u32 s11, s47, 0
	s_add_i32 s64, s65, s19
	global_load_lds_dwordx4 v[218:219], off
	v_lshl_add_u64 v[220:221], s[10:11], 0, v[136:137]
	s_mov_b32 m0, s64
	v_lshl_add_u64 v[222:223], s[48:49], 0, v[134:135]
	global_load_lds_dwordx4 v[220:221], off
	v_lshl_add_u64 v[220:221], s[10:11], 0, v[132:133]
	s_add_i32 m0, s64, 0x2000
	s_nop 0
	global_load_lds_dwordx4 v[220:221], off
	v_lshl_add_u64 v[220:221], s[48:49], 0, v[138:139]
	s_mov_b32 m0, s51
	s_nop 0
	global_load_lds_dwordx4 v[220:221], off
	s_mov_b32 m0, s52
	s_nop 0
	global_load_lds_dwordx4 v[222:223], off
	s_waitcnt vmcnt(8)
	s_waitcnt lgkmcnt(0)
	s_setprio 1
	s_barrier
; #define PG8_STAGE(bufoff, gbase, voff) do { _Pragma("unroll") for (int _i = 0; _i < 2; ++_i) \
;         __builtin_amdgcn_global_load_lds((const unsigned*)((const char*)(gbase) + (voff)[_i]), (PG8_LAS unsigned*)(lds + (bufoff) + ldsw + _i * 8192), 16, 0, 0); } while (0)
; #define PG8_LDA(dst, b, h) do { _Pragma("unroll") for (int m = 0; m < 4; ++m) _Pragma("unroll") for (int k = 0; k < 2; ++k) dst[m][k] = *(const PG8_LAS bf16x8*)(lds + PG8_SA(b, h) + aoff + m * 2048 + k * 1024); } while (0)
; #define PG8_LDB(dst, b, h) do { _Pragma("unroll") for (int n = 0; n < 2; ++n) _Pragma("unroll") for (int k = 0; k < 2; ++k) dst[n][k] = *(const PG8_LAS bf16x8*)(lds + PG8_SB(b, h) + boff + n * 2048 + k * 1024); } while (0)
; #define PG8_MMA(ai, bj, At, Bt) do { __builtin_amdgcn_s_setprio(1); _Pragma("unroll") for (int m = 0; m < 4; ++m) _Pragma("unroll") for (int n = 0; n < 2; ++n) _Pragma("unroll") for (int k = 0; k < 2; ++k) \
;         acc[ai][bj][m][n] = __builtin_amdgcn_mfma_f32_16x16x32_bf16(Bt[n][k], At[m][k], acc[ai][bj][m][n], 0, 0, 0); __builtin_amdgcn_s_setprio(0); } while (0)
; #define PG8_WAIT_V(n) asm volatile("s_waitcnt vmcnt(" #n ")" ::: "memory")
; #define PG8_WAIT_L(n) asm volatile("s_waitcnt lgkmcnt(" #n ")" ::: "memory")
; #define PG8_BAR __builtin_amdgcn_s_barrier()
; #define PG8_SCHED __builtin_amdgcn_sched_barrier(0)
; template <class Epi, class Sched, bool ALIGN_EPI = false, bool SP2 = false>
; __device__ __forceinline__ void gemm_phase(PG8_LAS unsigned char* lds, const Gemm g, const Sched& S, const Epi& E) {
;     ...
;             PG8_WAIT_V(8); PG8_WAIT_L(0); PG8_BAR; PG8_MMA(1, 0, At, B0); PG8_MMA(1, 1, At, B1); PG8_BAR; PG8_SCHED;
;             PG8_LDB(B0, 1, 0); PG8_LDB(B1, 1, 1); PG8_SCHED; PG8_LDA(At, 1, 0); PG8_STAGE(PG8_SA(0, 1), a2 + hstep, voffA);
;             PG8_WAIT_V(8); PG8_WAIT_L(0); PG8_BAR; PG8_MMA(0, 0, At, B0); PG8_MMA(0, 1, At, B1); PG8_BAR; PG8_SCHED;
	v_mfma_f32_16x16x32_bf16 v[60:63], v[128:131], v[182:185], v[60:63]
	v_mfma_f32_16x16x32_bf16 v[52:55], v[158:161], v[182:185], v[52:55]
	v_mfma_f32_16x16x32_bf16 v[44:47], v[128:131], v[194:197], v[44:47]
	v_mfma_f32_16x16x32_bf16 v[36:39], v[158:161], v[194:197], v[36:39]
	v_mfma_f32_16x16x32_bf16 v[28:31], v[128:131], v[202:205], v[28:31]
	v_mfma_f32_16x16x32_bf16 v[20:23], v[158:161], v[202:205], v[20:23]
	v_mfma_f32_16x16x32_bf16 v[12:15], v[128:131], v[210:213], v[12:15]
	v_mfma_f32_16x16x32_bf16 v[4:7], v[158:161], v[210:213], v[4:7]
	v_mfma_f32_16x16x32_bf16 v[60:63], v[154:157], v[186:189], v[60:63]
	v_mfma_f32_16x16x32_bf16 v[52:55], v[162:165], v[186:189], v[52:55]
	v_mfma_f32_16x16x32_bf16 v[44:47], v[154:157], v[198:201], v[44:47]
	v_mfma_f32_16x16x32_bf16 v[36:39], v[162:165], v[198:201], v[36:39]
	v_mfma_f32_16x16x32_bf16 v[28:31], v[154:157], v[206:209], v[28:31]
	v_mfma_f32_16x16x32_bf16 v[20:23], v[162:165], v[206:209], v[20:23]
	v_mfma_f32_16x16x32_bf16 v[12:15], v[154:157], v[214:217], v[12:15]
	v_mfma_f32_16x16x32_bf16 v[4:7], v[162:165], v[214:217], v[4:7]
	s_setprio 0
	s_setprio 1
	v_mfma_f32_16x16x32_bf16 v[56:59], v[166:169], v[182:185], v[56:59]
	v_mfma_f32_16x16x32_bf16 v[48:51], v[174:177], v[182:185], v[48:51]
	v_mfma_f32_16x16x32_bf16 v[40:43], v[166:169], v[194:197], v[40:43]
	v_mfma_f32_16x16x32_bf16 v[32:35], v[174:177], v[194:197], v[32:35]
	v_mfma_f32_16x16x32_bf16 v[24:27], v[166:169], v[202:205], v[24:27]
	v_mfma_f32_16x16x32_bf16 v[16:19], v[174:177], v[202:205], v[16:19]
	v_mfma_f32_16x16x32_bf16 v[8:11], v[166:169], v[210:213], v[8:11]
	v_mfma_f32_16x16x32_bf16 v[0:3], v[174:177], v[210:213], v[0:3]
	v_mfma_f32_16x16x32_bf16 v[56:59], v[170:173], v[186:189], v[56:59]
	v_mfma_f32_16x16x32_bf16 v[48:51], v[178:181], v[186:189], v[48:51]
	v_mfma_f32_16x16x32_bf16 v[40:43], v[170:173], v[198:201], v[40:43]
	v_mfma_f32_16x16x32_bf16 v[32:35], v[178:181], v[198:201], v[32:35]
	v_mfma_f32_16x16x32_bf16 v[24:27], v[170:173], v[206:209], v[24:27]
	v_mfma_f32_16x16x32_bf16 v[16:19], v[178:181], v[206:209], v[16:19]
	v_mfma_f32_16x16x32_bf16 v[8:11], v[170:173], v[214:217], v[8:11]
	v_mfma_f32_16x16x32_bf16 v[0:3], v[178:181], v[214:217], v[0:3]
	s_barrier
	s_setprio 0
	s_add_i32 s64, 0, 0x18000
	v_add_u32_e32 v146, s64, v149
	s_add_i32 s65, 0, 0x1c000
	ds_read_b128 v[128:131], v146
	ds_read_b128 v[154:157], v146 offset:1024
	ds_read_b128 v[158:161], v146 offset:2048
	ds_read_b128 v[162:165], v146 offset:3072
	v_add_u32_e32 v146, s65, v149
	ds_read_b128 v[166:169], v146
	ds_read_b128 v[170:173], v146 offset:1024
	ds_read_b128 v[174:177], v146 offset:2048
	ds_read_b128 v[178:181], v146 offset:3072
	s_add_u32 s10, s48, 0x40000
	s_addc_u32 s11, s49, 0
	s_mov_b32 m0, s53
	v_lshl_add_u64 v[224:225], s[10:11], 0, v[138:139]
	ds_read_b128 v[182:185], v153 offset:32768
	ds_read_b128 v[186:189], v153 offset:33792
	ds_read_b128 v[194:197], v153 offset:34816
	ds_read_b128 v[198:201], v153 offset:35840
	ds_read_b128 v[202:205], v153 offset:36864
	ds_read_b128 v[206:209], v153 offset:37888
	ds_read_b128 v[210:213], v153 offset:38912
	ds_read_b128 v[214:217], v153 offset:39936
	global_load_lds_dwordx4 v[224:225], off
	v_lshl_add_u64 v[224:225], s[10:11], 0, v[134:135]
	s_mov_b32 m0, s54
	s_nop 0
	global_load_lds_dwordx4 v[224:225], off
	s_waitcnt vmcnt(8)
	s_waitcnt lgkmcnt(0)
	s_setprio 1
	s_barrier
	v_mfma_f32_16x16x32_bf16 v[124:127], v[128:131], v[182:185], v[124:127]
	v_mfma_f32_16x16x32_bf16 v[116:119], v[158:161], v[182:185], v[116:119]
	v_mfma_f32_16x16x32_bf16 v[108:111], v[128:131], v[194:197], v[108:111]
	v_mfma_f32_16x16x32_bf16 v[100:103], v[158:161], v[194:197], v[100:103]
	v_mfma_f32_16x16x32_bf16 v[92:95], v[128:131], v[202:205], v[92:95]
	v_mfma_f32_16x16x32_bf16 v[84:87], v[158:161], v[202:205], v[84:87]
	v_mfma_f32_16x16x32_bf16 v[76:79], v[128:131], v[210:213], v[76:79]
	v_mfma_f32_16x16x32_bf16 v[68:71], v[158:161], v[210:213], v[68:71]
	v_mfma_f32_16x16x32_bf16 v[124:127], v[154:157], v[186:189], v[124:127]
	v_mfma_f32_16x16x32_bf16 v[116:119], v[162:165], v[186:189], v[116:119]
	v_mfma_f32_16x16x32_bf16 v[108:111], v[154:157], v[198:201], v[108:111]
	v_mfma_f32_16x16x32_bf16 v[100:103], v[162:165], v[198:201], v[100:103]
	v_mfma_f32_16x16x32_bf16 v[92:95], v[154:157], v[206:209], v[92:95]
	v_mfma_f32_16x16x32_bf16 v[84:87], v[162:165], v[206:209], v[84:87]
	v_mfma_f32_16x16x32_bf16 v[76:79], v[154:157], v[214:217], v[76:79]
	v_mfma_f32_16x16x32_bf16 v[68:71], v[162:165], v[214:217], v[68:71]
	s_setprio 0
	s_setprio 1
	v_mfma_f32_16x16x32_bf16 v[120:123], v[166:169], v[182:185], v[120:123]
	v_mfma_f32_16x16x32_bf16 v[112:115], v[174:177], v[182:185], v[112:115]
	v_mfma_f32_16x16x32_bf16 v[104:107], v[166:169], v[194:197], v[104:107]
	v_mfma_f32_16x16x32_bf16 v[96:99], v[174:177], v[194:197], v[96:99]
	v_mfma_f32_16x16x32_bf16 v[88:91], v[166:169], v[202:205], v[88:91]
	v_mfma_f32_16x16x32_bf16 v[80:83], v[174:177], v[202:205], v[80:83]
	v_mfma_f32_16x16x32_bf16 v[72:75], v[166:169], v[210:213], v[72:75]
	v_mfma_f32_16x16x32_bf16 v[64:67], v[174:177], v[210:213], v[64:67]
	v_mfma_f32_16x16x32_bf16 v[120:123], v[170:173], v[186:189], v[120:123]
	v_mfma_f32_16x16x32_bf16 v[112:115], v[178:181], v[186:189], v[112:115]
	v_mfma_f32_16x16x32_bf16 v[104:107], v[170:173], v[198:201], v[104:107]
	v_mfma_f32_16x16x32_bf16 v[96:99], v[178:181], v[198:201], v[96:99]
	v_mfma_f32_16x16x32_bf16 v[88:91], v[170:173], v[206:209], v[88:91]
	v_mfma_f32_16x16x32_bf16 v[80:83], v[178:181], v[206:209], v[80:83]
	v_mfma_f32_16x16x32_bf16 v[72:75], v[170:173], v[214:217], v[72:75]
	v_mfma_f32_16x16x32_bf16 v[64:67], v[178:181], v[214:217], v[64:67]
	s_barrier
; #define PG8_STAGE(bufoff, gbase, voff) do { _Pragma("unroll") for (int _i = 0; _i < 2; ++_i) \
;         __builtin_amdgcn_global_load_lds((const unsigned*)((const char*)(gbase) + (voff)[_i]), (PG8_LAS unsigned*)(lds + (bufoff) + ldsw + _i * 8192), 16, 0, 0); } while (0)
; #define PG8_LDA(dst, b, h) do { _Pragma("unroll") for (int m = 0; m < 4; ++m) _Pragma("unroll") for (int k = 0; k < 2; ++k) dst[m][k] = *(const PG8_LAS bf16x8*)(lds + PG8_SA(b, h) + aoff + m * 2048 + k * 1024); } while (0)
; #define PG8_MMA(ai, bj, At, Bt) do { __builtin_amdgcn_s_setprio(1); _Pragma("unroll") for (int m = 0; m < 4; ++m) _Pragma("unroll") for (int n = 0; n < 2; ++n) _Pragma("unroll") for (int k = 0; k < 2; ++k) \
;         acc[ai][bj][m][n] = __builtin_amdgcn_mfma_f32_16x16x32_bf16(Bt[n][k], At[m][k], acc[ai][bj][m][n], 0, 0, 0); __builtin_amdgcn_s_setprio(0); } while (0)
; #define PG8_WAIT_V(n) asm volatile("s_waitcnt vmcnt(" #n ")" ::: "memory")
; #define PG8_WAIT_L(n) asm volatile("s_waitcnt lgkmcnt(" #n ")" ::: "memory")
; #define PG8_BAR __builtin_amdgcn_s_barrier()
; #define PG8_SCHED __builtin_amdgcn_sched_barrier(0)
; template <class Epi, class Sched, bool ALIGN_EPI = false, bool SP2 = false>
; __device__ __forceinline__ void gemm_phase(PG8_LAS unsigned char* lds, const Gemm g, const Sched& S, const Epi& E) {
;     ...
;         for (int t = 0; t < nt; t += 2) {
;             const bool last = (t == nt - 2);
;             const char* a1 = cA + (size_t)(t + 1) * kstep;
;     ...
;             PG8_LDA(At, 1, 1); PG8_STAGE(PG8_SB(1, 0), b3, voffB); PG8_STAGE(PG8_SB(1, 1), b3 + hstep, voffB); PG8_STAGE(PG8_SA(1, 0), a3, voffA);
;             PG8_WAIT_V(8); PG8_WAIT_L(0); PG8_BAR; PG8_MMA(1, 0, At, B0); PG8_MMA(1, 1, At, B1); PG8_BAR; PG8_SCHED;
	s_setprio 0
	s_add_i32 s10, s64, s19
	v_lshl_add_u64 v[190:191], v[190:191], 0, s[36:37]
	s_mov_b32 m0, s10
	ds_read_b128 v[182:185], v153 offset:49152
	ds_read_b128 v[186:189], v153 offset:50176
	ds_read_b128 v[194:197], v153 offset:51200
	ds_read_b128 v[198:201], v153 offset:52224
	ds_read_b128 v[202:205], v153 offset:53248
	ds_read_b128 v[206:209], v153 offset:54272
	ds_read_b128 v[210:213], v153 offset:55296
	ds_read_b128 v[214:217], v153 offset:56320
	global_load_lds_dwordx4 v[190:191], off
	s_add_i32 m0, s10, 0x2000
	s_add_u32 s10, s46, 0x40080
	v_lshl_add_u64 v[190:191], v[218:219], 0, s[36:37]
	s_addc_u32 s11, s47, 0
	s_add_i32 s46, s65, s19
	global_load_lds_dwordx4 v[190:191], off
	v_lshl_add_u64 v[190:191], s[10:11], 0, v[136:137]
	s_mov_b32 m0, s46
	s_nop 0
	global_load_lds_dwordx4 v[190:191], off
	v_lshl_add_u64 v[190:191], s[10:11], 0, v[132:133]
	s_add_i32 m0, s46, 0x2000
	s_nop 0
	global_load_lds_dwordx4 v[190:191], off
	v_lshl_add_u64 v[190:191], v[220:221], 0, s[36:37]
	s_mov_b32 m0, s20
	s_nop 0
	global_load_lds_dwordx4 v[190:191], off
	v_lshl_add_u64 v[190:191], v[222:223], 0, s[36:37]
	s_mov_b32 m0, s55
	s_nop 0
	global_load_lds_dwordx4 v[190:191], off
	s_waitcnt vmcnt(8)
	s_waitcnt lgkmcnt(0)
	s_setprio 1
	s_barrier
	v_mfma_f32_16x16x32_bf16 v[60:63], v[128:131], v[182:185], v[60:63]
	v_mfma_f32_16x16x32_bf16 v[52:55], v[158:161], v[182:185], v[52:55]
	v_mfma_f32_16x16x32_bf16 v[44:47], v[128:131], v[194:197], v[44:47]
	v_mfma_f32_16x16x32_bf16 v[36:39], v[158:161], v[194:197], v[36:39]
	v_mfma_f32_16x16x32_bf16 v[28:31], v[128:131], v[202:205], v[28:31]
	v_mfma_f32_16x16x32_bf16 v[20:23], v[158:161], v[202:205], v[20:23]
	v_mfma_f32_16x16x32_bf16 v[12:15], v[128:131], v[210:213], v[12:15]
	v_mfma_f32_16x16x32_bf16 v[4:7], v[158:161], v[210:213], v[4:7]
	v_mfma_f32_16x16x32_bf16 v[60:63], v[154:157], v[186:189], v[60:63]
	v_mfma_f32_16x16x32_bf16 v[52:55], v[162:165], v[186:189], v[52:55]
	v_mfma_f32_16x16x32_bf16 v[44:47], v[154:157], v[198:201], v[44:47]
	v_mfma_f32_16x16x32_bf16 v[36:39], v[162:165], v[198:201], v[36:39]
	v_mfma_f32_16x16x32_bf16 v[28:31], v[154:157], v[206:209], v[28:31]
	v_mfma_f32_16x16x32_bf16 v[20:23], v[162:165], v[206:209], v[20:23]
	v_mfma_f32_16x16x32_bf16 v[12:15], v[154:157], v[214:217], v[12:15]
	v_mfma_f32_16x16x32_bf16 v[4:7], v[162:165], v[214:217], v[4:7]
	s_setprio 0
	s_setprio 1
	v_mfma_f32_16x16x32_bf16 v[56:59], v[166:169], v[182:185], v[56:59]
	v_mfma_f32_16x16x32_bf16 v[48:51], v[174:177], v[182:185], v[48:51]
	v_mfma_f32_16x16x32_bf16 v[40:43], v[166:169], v[194:197], v[40:43]
	v_mfma_f32_16x16x32_bf16 v[32:35], v[174:177], v[194:197], v[32:35]
	v_mfma_f32_16x16x32_bf16 v[24:27], v[166:169], v[202:205], v[24:27]
	v_mfma_f32_16x16x32_bf16 v[16:19], v[174:177], v[202:205], v[16:19]
	v_mfma_f32_16x16x32_bf16 v[8:11], v[166:169], v[210:213], v[8:11]
	v_mfma_f32_16x16x32_bf16 v[0:3], v[174:177], v[210:213], v[0:3]
	v_mfma_f32_16x16x32_bf16 v[56:59], v[170:173], v[186:189], v[56:59]
	v_mfma_f32_16x16x32_bf16 v[48:51], v[178:181], v[186:189], v[48:51]
	v_mfma_f32_16x16x32_bf16 v[40:43], v[170:173], v[198:201], v[40:43]
	v_mfma_f32_16x16x32_bf16 v[32:35], v[178:181], v[198:201], v[32:35]
	v_mfma_f32_16x16x32_bf16 v[24:27], v[170:173], v[206:209], v[24:27]
	v_mfma_f32_16x16x32_bf16 v[16:19], v[178:181], v[206:209], v[16:19]
	v_mfma_f32_16x16x32_bf16 v[8:11], v[170:173], v[214:217], v[8:11]
	v_mfma_f32_16x16x32_bf16 v[0:3], v[178:181], v[214:217], v[0:3]
	s_barrier
	s_setprio 0
	s_add_i32 s63, s63, 2
	s_add_u32 s44, s44, 0x100
	s_addc_u32 s45, s45, 0
	s_add_u32 s61, s61, 0x100
	s_addc_u32 s62, s62, 0
	s_cmp_gt_u32 s63, 13
	s_cbranch_scc0 .LBB0_577
	s_and_b64 vcc, exec, s[24:25]
	s_cbranch_vccz .LBB0_580
	s_barrier
